# six GEMM K-loop headers aligned to 64 bytes (s_nop padding outside the loops)
# speedup vs baseline: 1.0021x; 1.0010x over previous
; #define PG8_STAGE(bufoff, gbase, voff) do { _Pragma("unroll") for (int _i = 0; _i < 2; ++_i) \
;         __builtin_amdgcn_global_load_lds((const unsigned*)((const char*)(gbase) + (voff)[_i]), (PG8_LAS unsigned*)(lds + (bufoff) + ldsw + _i * 8192), 16, 0, 0); } while (0)
; #define PG8_LDA(dst, b, h) do { _Pragma("unroll") for (int m = 0; m < 4; ++m) _Pragma("unroll") for (int k = 0; k < 2; ++k) dst[m][k] = *(const PG8_LAS bf16x8*)(lds + PG8_SA(b, h) + aoff + m * 2048 + k * 1024); } while (0)
; #define PG8_LDB(dst, b, h) do { _Pragma("unroll") for (int n = 0; n < 2; ++n) _Pragma("unroll") for (int k = 0; k < 2; ++k) dst[n][k] = *(const PG8_LAS bf16x8*)(lds + PG8_SB(b, h) + boff + n * 2048 + k * 1024); } while (0)
; #define PG8_MMA(ai, bj, At, Bt) do { __builtin_amdgcn_s_setprio(1); _Pragma("unroll") for (int m = 0; m < 4; ++m) _Pragma("unroll") for (int n = 0; n < 2; ++n) _Pragma("unroll") for (int k = 0; k < 2; ++k) \
;         acc[ai][bj][m][n] = __builtin_amdgcn_mfma_f32_16x16x32_bf16(Bt[n][k], At[m][k], acc[ai][bj][m][n], 0, 0, 0); __builtin_amdgcn_s_setprio(0); } while (0)
; #define PG8_WAIT_V(n) asm volatile("s_waitcnt vmcnt(" #n ")" ::: "memory")
; #define PG8_WAIT_L(n) asm volatile("s_waitcnt lgkmcnt(" #n ")" ::: "memory")
; #define PG8_BAR __builtin_amdgcn_s_barrier()
; #define PG8_SCHED __builtin_amdgcn_sched_barrier(0)
; template <class Epi, class Sched, bool ALIGN_EPI = false, bool SP2 = false>
; __device__ __forceinline__ void gemm_phase(PG8_LAS unsigned char* lds, const Gemm g, const Sched& S, const Epi& E) {
;     ...
;             PG8_LDB(B0, 0, 0); PG8_LDB(B1, 0, 1); PG8_SCHED; PG8_LDA(At, 0, 0); PG8_STAGE(PG8_SA(1, 1), a1 + hstep, voffA);
;             PG8_WAIT_V(8); PG8_WAIT_L(0); PG8_BAR; PG8_MMA(0, 0, At, B0); PG8_MMA(0, 1, At, B1); PG8_BAR; PG8_SCHED;
;             PG8_LDA(At, 0, 1); PG8_STAGE(PG8_SB(0, 0), b2, voffB); PG8_STAGE(PG8_SB(0, 1), b2 + hstep, voffB); PG8_STAGE(PG8_SA(0, 0), a2, voffA);
;             PG8_WAIT_V(8); PG8_WAIT_L(0); PG8_BAR; PG8_MMA(1, 0, At, B0); PG8_MMA(1, 1, At, B1); PG8_BAR; PG8_SCHED;
.Lp1_plain:
	ds_read_b128 v[150:153], v147
	ds_read_b128 v[154:157], v147 offset:1024
	ds_read_b128 v[158:161], v147 offset:2048
	ds_read_b128 v[162:165], v147 offset:3072
	ds_read_b128 v[166:169], v148
	ds_read_b128 v[170:173], v148 offset:1024
	ds_read_b128 v[174:177], v148 offset:2048
	ds_read_b128 v[178:181], v148 offset:3072
	s_add_u32 s24, s22, 0xfffc0080
	s_addc_u32 s25, s23, -1
	s_cmp_eq_u32 s54, 12
	s_cselect_b32 s31, s15, s25
	s_cselect_b32 s30, s50, s24
	s_cselect_b32 s25, s9, s53
	s_cselect_b32 s24, s51, s52
	v_lshl_add_u64 v[186:187], s[22:23], 0, v[136:137]
	s_add_i32 m0, s21, 0xc000
	ds_read_b128 v[182:185], v149
	ds_read_b128 v[192:195], v149 offset:1024
	ds_read_b128 v[196:199], v149 offset:2048
	ds_read_b128 v[200:203], v149 offset:3072
	ds_read_b128 v[204:207], v149 offset:4096
	ds_read_b128 v[208:211], v149 offset:5120
	ds_read_b128 v[212:215], v149 offset:6144
	ds_read_b128 v[216:219], v149 offset:7168
	global_load_lds_dwordx4 v[186:187], off
	v_lshl_add_u64 v[186:187], s[22:23], 0, v[138:139]
	s_add_i32 m0, s21, 0xe000
	s_nop 0
	global_load_lds_dwordx4 v[186:187], off
	s_waitcnt vmcnt(16)
	s_waitcnt lgkmcnt(0)
	s_barrier
	s_setprio 1
	v_mfma_f32_16x16x32_bf16 v[124:127], v[150:153], v[182:185], 0
	v_mfma_f32_16x16x32_bf16 v[120:123], v[158:161], v[182:185], 0
	v_mfma_f32_16x16x32_bf16 v[108:111], v[150:153], v[196:199], 0
	v_mfma_f32_16x16x32_bf16 v[104:107], v[158:161], v[196:199], 0
	v_mfma_f32_16x16x32_bf16 v[92:95], v[150:153], v[204:207], 0
	v_mfma_f32_16x16x32_bf16 v[88:91], v[158:161], v[204:207], 0
	v_mfma_f32_16x16x32_bf16 v[76:79], v[150:153], v[212:215], 0
	v_mfma_f32_16x16x32_bf16 v[72:75], v[158:161], v[212:215], 0
	v_mfma_f32_16x16x32_bf16 v[124:127], v[154:157], v[192:195], v[124:127]
	v_mfma_f32_16x16x32_bf16 v[120:123], v[162:165], v[192:195], v[120:123]
	v_mfma_f32_16x16x32_bf16 v[108:111], v[154:157], v[200:203], v[108:111]
	v_mfma_f32_16x16x32_bf16 v[104:107], v[162:165], v[200:203], v[104:107]
	v_mfma_f32_16x16x32_bf16 v[92:95], v[154:157], v[208:211], v[92:95]
	v_mfma_f32_16x16x32_bf16 v[88:91], v[162:165], v[208:211], v[88:91]
	v_mfma_f32_16x16x32_bf16 v[76:79], v[154:157], v[216:219], v[76:79]
	v_mfma_f32_16x16x32_bf16 v[72:75], v[162:165], v[216:219], v[72:75]
	v_mfma_f32_16x16x32_bf16 v[116:119], v[166:169], v[182:185], 0
	v_mfma_f32_16x16x32_bf16 v[112:115], v[174:177], v[182:185], 0
	v_mfma_f32_16x16x32_bf16 v[100:103], v[166:169], v[196:199], 0
	v_mfma_f32_16x16x32_bf16 v[96:99], v[174:177], v[196:199], 0
	v_mfma_f32_16x16x32_bf16 v[84:87], v[166:169], v[204:207], 0
	v_mfma_f32_16x16x32_bf16 v[80:83], v[174:177], v[204:207], 0
	v_mfma_f32_16x16x32_bf16 v[68:71], v[166:169], v[212:215], 0
	v_mfma_f32_16x16x32_bf16 v[64:67], v[174:177], v[212:215], 0
	v_mfma_f32_16x16x32_bf16 v[116:119], v[170:173], v[192:195], v[116:119]
	v_mfma_f32_16x16x32_bf16 v[112:115], v[178:181], v[192:195], v[112:115]
	v_mfma_f32_16x16x32_bf16 v[100:103], v[170:173], v[200:203], v[100:103]
	v_mfma_f32_16x16x32_bf16 v[96:99], v[178:181], v[200:203], v[96:99]
	v_mfma_f32_16x16x32_bf16 v[84:87], v[170:173], v[208:211], v[84:87]
	v_mfma_f32_16x16x32_bf16 v[80:83], v[178:181], v[208:211], v[80:83]
	v_mfma_f32_16x16x32_bf16 v[68:71], v[170:173], v[216:219], v[68:71]
	v_mfma_f32_16x16x32_bf16 v[64:67], v[178:181], v[216:219], v[64:67]
	s_setprio 0
	s_barrier
	s_add_i32 s55, s46, s35
	v_lshl_add_u64 v[186:187], s[24:25], 0, v[132:133]
	s_mov_b32 m0, s55
	ds_read_b128 v[182:185], v149 offset:16384
	ds_read_b128 v[192:195], v149 offset:17408
	ds_read_b128 v[196:199], v149 offset:18432
	ds_read_b128 v[200:203], v149 offset:19456
	ds_read_b128 v[204:207], v149 offset:20480
	ds_read_b128 v[208:211], v149 offset:21504
	ds_read_b128 v[212:215], v149 offset:22528
	ds_read_b128 v[216:219], v149 offset:23552
	global_load_lds_dwordx4 v[186:187], off
	s_add_i32 m0, s55, 0x2000
	s_add_u32 s56, s24, 0x40000
	v_lshl_add_u64 v[220:221], s[24:25], 0, v[128:129]
	s_addc_u32 s57, s25, 0
	s_add_i32 s55, s47, s35
	global_load_lds_dwordx4 v[220:221], off
	v_lshl_add_u64 v[222:223], s[56:57], 0, v[132:133]
	s_mov_b32 m0, s55
	v_lshl_add_u64 v[224:225], s[30:31], 0, v[130:131]
	global_load_lds_dwordx4 v[222:223], off
	v_lshl_add_u64 v[222:223], s[56:57], 0, v[128:129]
	s_add_i32 m0, s55, 0x2000
	s_nop 0
	global_load_lds_dwordx4 v[222:223], off
	v_lshl_add_u64 v[222:223], s[30:31], 0, v[134:135]
	s_mov_b32 m0, s21
	s_nop 0
	global_load_lds_dwordx4 v[222:223], off
	s_mov_b32 m0, s38
	s_nop 0
	global_load_lds_dwordx4 v[224:225], off
	s_waitcnt vmcnt(16)
	s_waitcnt lgkmcnt(0)
	s_barrier
	s_setprio 1
	v_mfma_f32_16x16x32_bf16 v[60:63], v[150:153], v[182:185], 0
	v_mfma_f32_16x16x32_bf16 v[56:59], v[158:161], v[182:185], 0
	v_mfma_f32_16x16x32_bf16 v[44:47], v[150:153], v[196:199], 0
	v_mfma_f32_16x16x32_bf16 v[40:43], v[158:161], v[196:199], 0
	v_mfma_f32_16x16x32_bf16 v[28:31], v[150:153], v[204:207], 0
	v_mfma_f32_16x16x32_bf16 v[24:27], v[158:161], v[204:207], 0
	v_mfma_f32_16x16x32_bf16 v[12:15], v[150:153], v[212:215], 0
	v_mfma_f32_16x16x32_bf16 v[8:11], v[158:161], v[212:215], 0
	v_mfma_f32_16x16x32_bf16 v[60:63], v[154:157], v[192:195], v[60:63]
	v_mfma_f32_16x16x32_bf16 v[56:59], v[162:165], v[192:195], v[56:59]
	v_mfma_f32_16x16x32_bf16 v[44:47], v[154:157], v[200:203], v[44:47]
	v_mfma_f32_16x16x32_bf16 v[40:43], v[162:165], v[200:203], v[40:43]
	v_mfma_f32_16x16x32_bf16 v[28:31], v[154:157], v[208:211], v[28:31]
	v_mfma_f32_16x16x32_bf16 v[24:27], v[162:165], v[208:211], v[24:27]
	v_mfma_f32_16x16x32_bf16 v[12:15], v[154:157], v[216:219], v[12:15]
	v_mfma_f32_16x16x32_bf16 v[8:11], v[162:165], v[216:219], v[8:11]
	v_mfma_f32_16x16x32_bf16 v[52:55], v[166:169], v[182:185], 0
	v_mfma_f32_16x16x32_bf16 v[48:51], v[174:177], v[182:185], 0
	v_mfma_f32_16x16x32_bf16 v[36:39], v[166:169], v[196:199], 0
	v_mfma_f32_16x16x32_bf16 v[32:35], v[174:177], v[196:199], 0
	v_mfma_f32_16x16x32_bf16 v[20:23], v[166:169], v[204:207], 0
	v_mfma_f32_16x16x32_bf16 v[16:19], v[174:177], v[204:207], 0
	v_mfma_f32_16x16x32_bf16 v[4:7], v[166:169], v[212:215], 0
	v_mfma_f32_16x16x32_bf16 v[0:3], v[174:177], v[212:215], 0
	v_mfma_f32_16x16x32_bf16 v[52:55], v[170:173], v[192:195], v[52:55]
	v_mfma_f32_16x16x32_bf16 v[48:51], v[178:181], v[192:195], v[48:51]
	v_mfma_f32_16x16x32_bf16 v[36:39], v[170:173], v[200:203], v[36:39]
	v_mfma_f32_16x16x32_bf16 v[32:35], v[178:181], v[200:203], v[32:35]
	v_mfma_f32_16x16x32_bf16 v[20:23], v[170:173], v[208:211], v[20:23]
	v_mfma_f32_16x16x32_bf16 v[16:19], v[178:181], v[208:211], v[16:19]
	v_mfma_f32_16x16x32_bf16 v[4:7], v[170:173], v[216:219], v[4:7]
	v_mfma_f32_16x16x32_bf16 v[0:3], v[178:181], v[216:219], v[0:3]
	s_setprio 0
	s_barrier
; #define PG8_STAGE(bufoff, gbase, voff) do { _Pragma("unroll") for (int _i = 0; _i < 2; ++_i) \
;         __builtin_amdgcn_global_load_lds((const unsigned*)((const char*)(gbase) + (voff)[_i]), (PG8_LAS unsigned*)(lds + (bufoff) + ldsw + _i * 8192), 16, 0, 0); } while (0)
; #define PG8_LDA(dst, b, h) do { _Pragma("unroll") for (int m = 0; m < 4; ++m) _Pragma("unroll") for (int k = 0; k < 2; ++k) dst[m][k] = *(const PG8_LAS bf16x8*)(lds + PG8_SA(b, h) + aoff + m * 2048 + k * 1024); } while (0)
; #define PG8_LDB(dst, b, h) do { _Pragma("unroll") for (int n = 0; n < 2; ++n) _Pragma("unroll") for (int k = 0; k < 2; ++k) dst[n][k] = *(const PG8_LAS bf16x8*)(lds + PG8_SB(b, h) + boff + n * 2048 + k * 1024); } while (0)
; #define PG8_MMA(ai, bj, At, Bt) do { __builtin_amdgcn_s_setprio(1); _Pragma("unroll") for (int m = 0; m < 4; ++m) _Pragma("unroll") for (int n = 0; n < 2; ++n) _Pragma("unroll") for (int k = 0; k < 2; ++k) \
;         acc[ai][bj][m][n] = __builtin_amdgcn_mfma_f32_16x16x32_bf16(Bt[n][k], At[m][k], acc[ai][bj][m][n], 0, 0, 0); __builtin_amdgcn_s_setprio(0); } while (0)
; #define PG8_WAIT_V(n) asm volatile("s_waitcnt vmcnt(" #n ")" ::: "memory")
; #define PG8_WAIT_L(n) asm volatile("s_waitcnt lgkmcnt(" #n ")" ::: "memory")
; #define PG8_BAR __builtin_amdgcn_s_barrier()
; #define PG8_SCHED __builtin_amdgcn_sched_barrier(0)
; template <class Epi, class Sched, bool ALIGN_EPI = false, bool SP2 = false>
; __device__ __forceinline__ void gemm_phase(PG8_LAS unsigned char* lds, const Gemm g, const Sched& S, const Epi& E) {
;     ...
;             PG8_LDB(B0, 1, 0); PG8_LDB(B1, 1, 1); PG8_SCHED; PG8_LDA(At, 1, 0); PG8_STAGE(PG8_SA(0, 1), a2 + hstep, voffA);
;             PG8_WAIT_V(8); PG8_WAIT_L(0); PG8_BAR; PG8_MMA(0, 0, At, B0); PG8_MMA(0, 1, At, B1); PG8_BAR; PG8_SCHED;
;             PG8_LDA(At, 1, 1); PG8_STAGE(PG8_SB(1, 0), b3, voffB); PG8_STAGE(PG8_SB(1, 1), b3 + hstep, voffB); PG8_STAGE(PG8_SA(1, 0), a3, voffA);
;             PG8_WAIT_V(8); PG8_WAIT_L(0); PG8_BAR; PG8_MMA(1, 0, At, B0); PG8_MMA(1, 1, At, B1); PG8_BAR; PG8_SCHED;
	s_add_i32 s55, 0, 0x18000
	s_add_i32 s56, 0, 0x1c000
	v_add_u32_e32 v162, s55, v145
	v_add_u32_e32 v178, s56, v145
	ds_read_b128 v[150:153], v162
	ds_read_b128 v[154:157], v162 offset:1024
	ds_read_b128 v[158:161], v162 offset:2048
	ds_read_b128 v[162:165], v162 offset:3072
	ds_read_b128 v[166:169], v178
	ds_read_b128 v[170:173], v178 offset:1024
	ds_read_b128 v[174:177], v178 offset:2048
	ds_read_b128 v[178:181], v178 offset:3072
	s_add_u32 s30, s30, 0x40000
	s_addc_u32 s31, s31, 0
	s_mov_b32 m0, s39
	v_lshl_add_u64 v[226:227], s[30:31], 0, v[134:135]
	ds_read_b128 v[182:185], v149 offset:32768
	ds_read_b128 v[192:195], v149 offset:33792
	ds_read_b128 v[196:199], v149 offset:34816
	ds_read_b128 v[200:203], v149 offset:35840
	ds_read_b128 v[204:207], v149 offset:36864
	ds_read_b128 v[208:211], v149 offset:37888
	ds_read_b128 v[212:215], v149 offset:38912
	ds_read_b128 v[216:219], v149 offset:39936
	global_load_lds_dwordx4 v[226:227], off
	v_lshl_add_u64 v[226:227], s[30:31], 0, v[130:131]
	s_mov_b32 m0, s40
	s_nop 0
	global_load_lds_dwordx4 v[226:227], off
	s_waitcnt vmcnt(8)
	s_waitcnt lgkmcnt(0)
	s_barrier
	s_setprio 1
	v_mfma_f32_16x16x32_bf16 v[124:127], v[150:153], v[182:185], v[124:127]
	v_mfma_f32_16x16x32_bf16 v[120:123], v[158:161], v[182:185], v[120:123]
	v_mfma_f32_16x16x32_bf16 v[108:111], v[150:153], v[196:199], v[108:111]
	v_mfma_f32_16x16x32_bf16 v[104:107], v[158:161], v[196:199], v[104:107]
	v_mfma_f32_16x16x32_bf16 v[92:95], v[150:153], v[204:207], v[92:95]
	v_mfma_f32_16x16x32_bf16 v[88:91], v[158:161], v[204:207], v[88:91]
	v_mfma_f32_16x16x32_bf16 v[76:79], v[150:153], v[212:215], v[76:79]
	v_mfma_f32_16x16x32_bf16 v[72:75], v[158:161], v[212:215], v[72:75]
	v_mfma_f32_16x16x32_bf16 v[124:127], v[154:157], v[192:195], v[124:127]
	v_mfma_f32_16x16x32_bf16 v[120:123], v[162:165], v[192:195], v[120:123]
	v_mfma_f32_16x16x32_bf16 v[108:111], v[154:157], v[200:203], v[108:111]
	v_mfma_f32_16x16x32_bf16 v[104:107], v[162:165], v[200:203], v[104:107]
	v_mfma_f32_16x16x32_bf16 v[92:95], v[154:157], v[208:211], v[92:95]
	v_mfma_f32_16x16x32_bf16 v[88:91], v[162:165], v[208:211], v[88:91]
	v_mfma_f32_16x16x32_bf16 v[76:79], v[154:157], v[216:219], v[76:79]
	v_mfma_f32_16x16x32_bf16 v[72:75], v[162:165], v[216:219], v[72:75]
	v_mfma_f32_16x16x32_bf16 v[116:119], v[166:169], v[182:185], v[116:119]
	v_mfma_f32_16x16x32_bf16 v[112:115], v[174:177], v[182:185], v[112:115]
	v_mfma_f32_16x16x32_bf16 v[100:103], v[166:169], v[196:199], v[100:103]
	v_mfma_f32_16x16x32_bf16 v[96:99], v[174:177], v[196:199], v[96:99]
	v_mfma_f32_16x16x32_bf16 v[84:87], v[166:169], v[204:207], v[84:87]
	v_mfma_f32_16x16x32_bf16 v[80:83], v[174:177], v[204:207], v[80:83]
	v_mfma_f32_16x16x32_bf16 v[68:71], v[166:169], v[212:215], v[68:71]
	v_mfma_f32_16x16x32_bf16 v[64:67], v[174:177], v[212:215], v[64:67]
	v_mfma_f32_16x16x32_bf16 v[116:119], v[170:173], v[192:195], v[116:119]
	v_mfma_f32_16x16x32_bf16 v[112:115], v[178:181], v[192:195], v[112:115]
	v_mfma_f32_16x16x32_bf16 v[100:103], v[170:173], v[200:203], v[100:103]
	v_mfma_f32_16x16x32_bf16 v[96:99], v[178:181], v[200:203], v[96:99]
	v_mfma_f32_16x16x32_bf16 v[84:87], v[170:173], v[208:211], v[84:87]
	v_mfma_f32_16x16x32_bf16 v[80:83], v[178:181], v[208:211], v[80:83]
	v_mfma_f32_16x16x32_bf16 v[68:71], v[170:173], v[216:219], v[68:71]
	v_mfma_f32_16x16x32_bf16 v[64:67], v[178:181], v[216:219], v[64:67]
	s_setprio 0
	s_barrier
	s_add_i32 s30, s55, s35
	v_lshl_add_u64 v[186:187], v[186:187], 0, s[4:5]
	s_mov_b32 m0, s30
	ds_read_b128 v[182:185], v149 offset:49152
	ds_read_b128 v[192:195], v149 offset:50176
	ds_read_b128 v[196:199], v149 offset:51200
	ds_read_b128 v[200:203], v149 offset:52224
	ds_read_b128 v[204:207], v149 offset:53248
	ds_read_b128 v[208:211], v149 offset:54272
	ds_read_b128 v[212:215], v149 offset:55296
	ds_read_b128 v[216:219], v149 offset:56320
	global_load_lds_dwordx4 v[186:187], off
	s_add_i32 m0, s30, 0x2000
	s_add_u32 s24, s24, 0x40080
	v_lshl_add_u64 v[186:187], v[220:221], 0, s[4:5]
	s_addc_u32 s25, s25, 0
	s_add_i32 s30, s56, s35
	global_load_lds_dwordx4 v[186:187], off
	v_lshl_add_u64 v[186:187], s[24:25], 0, v[132:133]
	s_mov_b32 m0, s30
	s_nop 0
	global_load_lds_dwordx4 v[186:187], off
	v_lshl_add_u64 v[186:187], s[24:25], 0, v[128:129]
	s_add_i32 m0, s30, 0x2000
	s_nop 0
	global_load_lds_dwordx4 v[186:187], off
	v_lshl_add_u64 v[186:187], v[222:223], 0, s[4:5]
	s_mov_b32 m0, s42
	s_nop 0
	global_load_lds_dwordx4 v[186:187], off
	v_lshl_add_u64 v[186:187], v[224:225], 0, s[4:5]
	s_mov_b32 m0, s43
	s_nop 0
	global_load_lds_dwordx4 v[186:187], off
	s_waitcnt vmcnt(8)
	s_waitcnt lgkmcnt(0)
	s_barrier
	s_setprio 1
	v_mfma_f32_16x16x32_bf16 v[60:63], v[150:153], v[182:185], v[60:63]
	v_mfma_f32_16x16x32_bf16 v[56:59], v[158:161], v[182:185], v[56:59]
	v_mfma_f32_16x16x32_bf16 v[44:47], v[150:153], v[196:199], v[44:47]
	v_mfma_f32_16x16x32_bf16 v[40:43], v[158:161], v[196:199], v[40:43]
	v_mfma_f32_16x16x32_bf16 v[28:31], v[150:153], v[204:207], v[28:31]
	v_mfma_f32_16x16x32_bf16 v[24:27], v[158:161], v[204:207], v[24:27]
	v_mfma_f32_16x16x32_bf16 v[12:15], v[150:153], v[212:215], v[12:15]
	v_mfma_f32_16x16x32_bf16 v[8:11], v[158:161], v[212:215], v[8:11]
	v_mfma_f32_16x16x32_bf16 v[60:63], v[154:157], v[192:195], v[60:63]
	v_mfma_f32_16x16x32_bf16 v[56:59], v[162:165], v[192:195], v[56:59]
	v_mfma_f32_16x16x32_bf16 v[44:47], v[154:157], v[200:203], v[44:47]
	v_mfma_f32_16x16x32_bf16 v[40:43], v[162:165], v[200:203], v[40:43]
	v_mfma_f32_16x16x32_bf16 v[28:31], v[154:157], v[208:211], v[28:31]
	v_mfma_f32_16x16x32_bf16 v[24:27], v[162:165], v[208:211], v[24:27]
	v_mfma_f32_16x16x32_bf16 v[12:15], v[154:157], v[216:219], v[12:15]
	v_mfma_f32_16x16x32_bf16 v[8:11], v[162:165], v[216:219], v[8:11]
	v_mfma_f32_16x16x32_bf16 v[52:55], v[166:169], v[182:185], v[52:55]
	v_mfma_f32_16x16x32_bf16 v[48:51], v[174:177], v[182:185], v[48:51]
	v_mfma_f32_16x16x32_bf16 v[36:39], v[166:169], v[196:199], v[36:39]
	v_mfma_f32_16x16x32_bf16 v[32:35], v[174:177], v[196:199], v[32:35]
	v_mfma_f32_16x16x32_bf16 v[20:23], v[166:169], v[204:207], v[20:23]
	v_mfma_f32_16x16x32_bf16 v[16:19], v[174:177], v[204:207], v[16:19]
	v_mfma_f32_16x16x32_bf16 v[4:7], v[166:169], v[212:215], v[4:7]
	v_mfma_f32_16x16x32_bf16 v[0:3], v[174:177], v[212:215], v[0:3]
	v_mfma_f32_16x16x32_bf16 v[52:55], v[170:173], v[192:195], v[52:55]
	v_mfma_f32_16x16x32_bf16 v[48:51], v[178:181], v[192:195], v[48:51]
	v_mfma_f32_16x16x32_bf16 v[36:39], v[170:173], v[200:203], v[36:39]
	v_mfma_f32_16x16x32_bf16 v[32:35], v[178:181], v[200:203], v[32:35]
	v_mfma_f32_16x16x32_bf16 v[20:23], v[170:173], v[208:211], v[20:23]
	v_mfma_f32_16x16x32_bf16 v[16:19], v[178:181], v[208:211], v[16:19]
	v_mfma_f32_16x16x32_bf16 v[4:7], v[170:173], v[216:219], v[4:7]
	v_mfma_f32_16x16x32_bf16 v[0:3], v[178:181], v[216:219], v[0:3]
	s_setprio 0
	s_barrier
	s_add_i32 s54, s54, 2
	s_add_u32 s22, s22, 0x100
	s_addc_u32 s23, s23, 0
	s_add_u32 s52, s52, 0x100
	s_addc_u32 s53, s53, 0
	.p2alignl 6, 3212836864

; #define PG8_STAGE(bufoff, gbase, voff) do { _Pragma("unroll") for (int _i = 0; _i < 2; ++_i) \
;         __builtin_amdgcn_global_load_lds((const unsigned*)((const char*)(gbase) + (voff)[_i]), (PG8_LAS unsigned*)(lds + (bufoff) + ldsw + _i * 8192), 16, 0, 0); } while (0)
; #define PG8_LDA(dst, b, h) do { _Pragma("unroll") for (int m = 0; m < 4; ++m) _Pragma("unroll") for (int k = 0; k < 2; ++k) dst[m][k] = *(const PG8_LAS bf16x8*)(lds + PG8_SA(b, h) + aoff + m * 2048 + k * 1024); } while (0)
; #define PG8_LDB(dst, b, h) do { _Pragma("unroll") for (int n = 0; n < 2; ++n) _Pragma("unroll") for (int k = 0; k < 2; ++k) dst[n][k] = *(const PG8_LAS bf16x8*)(lds + PG8_SB(b, h) + boff + n * 2048 + k * 1024); } while (0)
; #define PG8_WAIT_V(n) asm volatile("s_waitcnt vmcnt(" #n ")" ::: "memory")
; #define PG8_WAIT_L(n) asm volatile("s_waitcnt lgkmcnt(" #n ")" ::: "memory")
; #define PG8_BAR __builtin_amdgcn_s_barrier()
; #define PG8_SCHED __builtin_amdgcn_sched_barrier(0)
; template <class Epi, class Sched, bool ALIGN_EPI = false, bool SP2 = false>
; __device__ __forceinline__ void gemm_phase(PG8_LAS unsigned char* lds, const Gemm g, const Sched& S, const Epi& E) {
;     ...
;         const bool has_next = S.next(ui + 1, nxt);
;         const char* nA = has_next ? (const char*)g.A + (size_t)nxt.pm * tstep : cA; const char* nB = has_next ? (const char*)g.Bt + (size_t)nxt.pn * tstep : cB;
;         for (int t = 0; t < nt; t += 2) {
;             const bool last = (t == nt - 2);
;             const char* a1 = cA + (size_t)(t + 1) * kstep;
;             const char* a2 = last ? nA : cA + (size_t)(t + 2) * kstep; const char* b2 = last ? nB : cB + (size_t)(t + 2) * kstep;
;             const char* a3 = a2 + kstep; const char* b3 = b2 + kstep;
;             if (last && has_next) S.a_ready(nxt);
;             if constexpr (SP2) {
;             PG8_LDB(B0, 0, 0); PG8_LDB(B1, 0, 1); PG8_SCHED; PG8_LDA(At, 0, 0); PG8_STAGE(PG8_SA(1, 1), a1 + hstep, voffA);
;             PG8_WAIT_V(8); PG8_WAIT_L(0); PG8_BAR; PG8_MMA(0, 0, At, B0); PG8_MMA(0, 1, At, B1); PG8_BAR; PG8_SCHED;
;             PG8_LDA(At, 0, 1); PG8_STAGE(PG8_SB(0, 0), b2, voffB); PG8_STAGE(PG8_SB(0, 1), b2 + hstep, voffB); PG8_STAGE(PG8_SA(0, 0), a2, voffA);
;             PG8_WAIT_V(8); PG8_WAIT_L(0); PG8_BAR; PG8_MMA(1, 0, At, B0); PG8_MMA(1, 1, At, B1); PG8_BAR; PG8_SCHED;
.LBB0_273:
	s_add_u32 s58, s34, 0x100
	s_addc_u32 s59, s35, 0
	s_mov_b32 s60, -2
	s_waitcnt lgkmcnt(0)
	ds_read_b128 v[128:131], v161
	ds_read_b128 v[132:135], v161 offset:1024
	ds_read_b128 v[152:155], v161 offset:2048
	ds_read_b128 v[166:169], v161 offset:3072
	ds_read_b128 v[170:173], v162
	ds_read_b128 v[174:177], v162 offset:1024
	ds_read_b128 v[178:181], v162 offset:2048
	ds_read_b128 v[182:185], v162 offset:3072
	s_add_u32 s34, s8, 0x100
	s_addc_u32 s35, s9, 0
	s_cmp_eq_u32 s60, 40
	s_cselect_b32 s39, s1, s35
	s_cselect_b32 s38, s0, s34
	s_cselect_b32 s37, s31, s59
	s_cselect_b32 s36, s30, s58
	v_lshl_add_u64 v[156:157], s[8:9], 0, v[144:145]
	s_add_i32 m0, s42, 0xc000
	ds_read_b128 v[192:195], v163
	ds_read_b128 v[196:199], v163 offset:1024
	ds_read_b128 v[200:203], v163 offset:2048
	ds_read_b128 v[204:207], v163 offset:3072
	ds_read_b128 v[208:211], v163 offset:4096
	ds_read_b128 v[212:215], v163 offset:5120
	ds_read_b128 v[216:219], v163 offset:6144
	ds_read_b128 v[220:223], v163 offset:7168
	global_load_lds_dwordx4 v[156:157], off
	v_lshl_add_u64 v[156:157], s[8:9], 0, v[146:147]
	s_add_i32 m0, s42, 0xe000
	s_nop 0
	global_load_lds_dwordx4 v[156:157], off
	s_waitcnt vmcnt(8)
	s_waitcnt lgkmcnt(0)
	s_barrier
	s_setprio 1
	v_mfma_f32_16x16x32_bf16 v[124:127], v[128:131], v[192:195], 0
	v_mfma_f32_16x16x32_bf16 v[120:123], v[152:155], v[192:195], 0
	v_mfma_f32_16x16x32_bf16 v[108:111], v[128:131], v[200:203], 0
	v_mfma_f32_16x16x32_bf16 v[104:107], v[152:155], v[200:203], 0
	v_mfma_f32_16x16x32_bf16 v[92:95], v[128:131], v[208:211], 0
	v_mfma_f32_16x16x32_bf16 v[88:91], v[152:155], v[208:211], 0
	v_mfma_f32_16x16x32_bf16 v[76:79], v[128:131], v[216:219], 0
	v_mfma_f32_16x16x32_bf16 v[72:75], v[152:155], v[216:219], 0
	v_mfma_f32_16x16x32_bf16 v[124:127], v[132:135], v[196:199], v[124:127]
	v_mfma_f32_16x16x32_bf16 v[120:123], v[166:169], v[196:199], v[120:123]
	v_mfma_f32_16x16x32_bf16 v[108:111], v[132:135], v[204:207], v[108:111]
	v_mfma_f32_16x16x32_bf16 v[104:107], v[166:169], v[204:207], v[104:107]
	v_mfma_f32_16x16x32_bf16 v[92:95], v[132:135], v[212:215], v[92:95]
	v_mfma_f32_16x16x32_bf16 v[88:91], v[166:169], v[212:215], v[88:91]
	v_mfma_f32_16x16x32_bf16 v[76:79], v[132:135], v[220:223], v[76:79]
	v_mfma_f32_16x16x32_bf16 v[72:75], v[166:169], v[220:223], v[72:75]
	v_mfma_f32_16x16x32_bf16 v[116:119], v[170:173], v[192:195], 0
	v_mfma_f32_16x16x32_bf16 v[112:115], v[178:181], v[192:195], 0
	v_mfma_f32_16x16x32_bf16 v[100:103], v[170:173], v[200:203], 0
	v_mfma_f32_16x16x32_bf16 v[96:99], v[178:181], v[200:203], 0
	v_mfma_f32_16x16x32_bf16 v[84:87], v[170:173], v[208:211], 0
	v_mfma_f32_16x16x32_bf16 v[80:83], v[178:181], v[208:211], 0
	v_mfma_f32_16x16x32_bf16 v[68:71], v[170:173], v[216:219], 0
	v_mfma_f32_16x16x32_bf16 v[64:67], v[178:181], v[216:219], 0
	v_mfma_f32_16x16x32_bf16 v[116:119], v[174:177], v[196:199], v[116:119]
	v_mfma_f32_16x16x32_bf16 v[112:115], v[182:185], v[196:199], v[112:115]
	v_mfma_f32_16x16x32_bf16 v[100:103], v[174:177], v[204:207], v[100:103]
	v_mfma_f32_16x16x32_bf16 v[96:99], v[182:185], v[204:207], v[96:99]
	v_mfma_f32_16x16x32_bf16 v[84:87], v[174:177], v[212:215], v[84:87]
	v_mfma_f32_16x16x32_bf16 v[80:83], v[182:185], v[212:215], v[80:83]
	v_mfma_f32_16x16x32_bf16 v[68:71], v[174:177], v[220:223], v[68:71]
	v_mfma_f32_16x16x32_bf16 v[64:67], v[182:185], v[220:223], v[64:67]
	s_setprio 0
	s_barrier
	s_add_i32 s8, s52, s41
	v_lshl_add_u64 v[156:157], s[36:37], 0, v[138:139]
	s_mov_b32 m0, s8
	ds_read_b128 v[192:195], v163 offset:16384
	ds_read_b128 v[196:199], v163 offset:17408
	ds_read_b128 v[200:203], v163 offset:18432
	ds_read_b128 v[204:207], v163 offset:19456
	ds_read_b128 v[208:211], v163 offset:20480
	ds_read_b128 v[212:215], v163 offset:21504
	ds_read_b128 v[216:219], v163 offset:22528
	ds_read_b128 v[220:223], v163 offset:23552
	global_load_lds_dwordx4 v[156:157], off
	s_add_i32 m0, s8, 0x2000
	s_add_u32 s8, s36, 0xb0000
	v_lshl_add_u64 v[186:187], s[36:37], 0, v[142:143]
	s_addc_u32 s9, s37, 0
	s_add_i32 s61, s53, s41
	global_load_lds_dwordx4 v[186:187], off
	v_lshl_add_u64 v[224:225], s[8:9], 0, v[138:139]
	s_mov_b32 m0, s61
	v_lshl_add_u64 v[226:227], s[38:39], 0, v[140:141]
	global_load_lds_dwordx4 v[224:225], off
	v_lshl_add_u64 v[224:225], s[8:9], 0, v[142:143]
	s_add_i32 m0, s61, 0x2000
	s_nop 0
	global_load_lds_dwordx4 v[224:225], off
	v_lshl_add_u64 v[224:225], s[38:39], 0, v[136:137]
	s_mov_b32 m0, s42
	s_nop 0
	global_load_lds_dwordx4 v[224:225], off
	s_mov_b32 m0, s43
	s_nop 0
	global_load_lds_dwordx4 v[226:227], off
	s_waitcnt vmcnt(8)
	s_waitcnt lgkmcnt(0)
	s_barrier
; #define PG8_STAGE(bufoff, gbase, voff) do { _Pragma("unroll") for (int _i = 0; _i < 2; ++_i) \
;         __builtin_amdgcn_global_load_lds((const unsigned*)((const char*)(gbase) + (voff)[_i]), (PG8_LAS unsigned*)(lds + (bufoff) + ldsw + _i * 8192), 16, 0, 0); } while (0)
; #define PG8_LDA(dst, b, h) do { _Pragma("unroll") for (int m = 0; m < 4; ++m) _Pragma("unroll") for (int k = 0; k < 2; ++k) dst[m][k] = *(const PG8_LAS bf16x8*)(lds + PG8_SA(b, h) + aoff + m * 2048 + k * 1024); } while (0)
; #define PG8_LDB(dst, b, h) do { _Pragma("unroll") for (int n = 0; n < 2; ++n) _Pragma("unroll") for (int k = 0; k < 2; ++k) dst[n][k] = *(const PG8_LAS bf16x8*)(lds + PG8_SB(b, h) + boff + n * 2048 + k * 1024); } while (0)
; #define PG8_MMA(ai, bj, At, Bt) do { __builtin_amdgcn_s_setprio(1); _Pragma("unroll") for (int m = 0; m < 4; ++m) _Pragma("unroll") for (int n = 0; n < 2; ++n) _Pragma("unroll") for (int k = 0; k < 2; ++k) \
;         acc[ai][bj][m][n] = __builtin_amdgcn_mfma_f32_16x16x32_bf16(Bt[n][k], At[m][k], acc[ai][bj][m][n], 0, 0, 0); __builtin_amdgcn_s_setprio(0); } while (0)
; #define PG8_WAIT_V(n) asm volatile("s_waitcnt vmcnt(" #n ")" ::: "memory")
; #define PG8_WAIT_L(n) asm volatile("s_waitcnt lgkmcnt(" #n ")" ::: "memory")
; #define PG8_BAR __builtin_amdgcn_s_barrier()
; #define PG8_SCHED __builtin_amdgcn_sched_barrier(0)
; template <class Epi, class Sched, bool ALIGN_EPI = false, bool SP2 = false>
; __device__ __forceinline__ void gemm_phase(PG8_LAS unsigned char* lds, const Gemm g, const Sched& S, const Epi& E) {
;     ...
;             PG8_WAIT_V(8); PG8_WAIT_L(0); PG8_BAR; PG8_MMA(1, 0, At, B0); PG8_MMA(1, 1, At, B1); PG8_BAR; PG8_SCHED;
;             PG8_LDB(B0, 1, 0); PG8_LDB(B1, 1, 1); PG8_SCHED; PG8_LDA(At, 1, 0); PG8_STAGE(PG8_SA(0, 1), a2 + hstep, voffA);
;             PG8_WAIT_V(8); PG8_WAIT_L(0); PG8_BAR; PG8_MMA(0, 0, At, B0); PG8_MMA(0, 1, At, B1); PG8_BAR; PG8_SCHED;
	s_setprio 1
	v_mfma_f32_16x16x32_bf16 v[60:63], v[128:131], v[192:195], 0
	v_mfma_f32_16x16x32_bf16 v[56:59], v[152:155], v[192:195], 0
	v_mfma_f32_16x16x32_bf16 v[44:47], v[128:131], v[200:203], 0
	v_mfma_f32_16x16x32_bf16 v[40:43], v[152:155], v[200:203], 0
	v_mfma_f32_16x16x32_bf16 v[28:31], v[128:131], v[208:211], 0
	v_mfma_f32_16x16x32_bf16 v[24:27], v[152:155], v[208:211], 0
	v_mfma_f32_16x16x32_bf16 v[12:15], v[128:131], v[216:219], 0
	v_mfma_f32_16x16x32_bf16 v[8:11], v[152:155], v[216:219], 0
	v_mfma_f32_16x16x32_bf16 v[60:63], v[132:135], v[196:199], v[60:63]
	v_mfma_f32_16x16x32_bf16 v[56:59], v[166:169], v[196:199], v[56:59]
	v_mfma_f32_16x16x32_bf16 v[44:47], v[132:135], v[204:207], v[44:47]
	v_mfma_f32_16x16x32_bf16 v[40:43], v[166:169], v[204:207], v[40:43]
	v_mfma_f32_16x16x32_bf16 v[28:31], v[132:135], v[212:215], v[28:31]
	v_mfma_f32_16x16x32_bf16 v[24:27], v[166:169], v[212:215], v[24:27]
	v_mfma_f32_16x16x32_bf16 v[12:15], v[132:135], v[220:223], v[12:15]
	v_mfma_f32_16x16x32_bf16 v[8:11], v[166:169], v[220:223], v[8:11]
	v_mfma_f32_16x16x32_bf16 v[52:55], v[170:173], v[192:195], 0
	v_mfma_f32_16x16x32_bf16 v[48:51], v[178:181], v[192:195], 0
	v_mfma_f32_16x16x32_bf16 v[36:39], v[170:173], v[200:203], 0
	v_mfma_f32_16x16x32_bf16 v[32:35], v[178:181], v[200:203], 0
	v_mfma_f32_16x16x32_bf16 v[20:23], v[170:173], v[208:211], 0
	v_mfma_f32_16x16x32_bf16 v[16:19], v[178:181], v[208:211], 0
	v_mfma_f32_16x16x32_bf16 v[4:7], v[170:173], v[216:219], 0
	v_mfma_f32_16x16x32_bf16 v[0:3], v[178:181], v[216:219], 0
	v_mfma_f32_16x16x32_bf16 v[52:55], v[174:177], v[196:199], v[52:55]
	v_mfma_f32_16x16x32_bf16 v[48:51], v[182:185], v[196:199], v[48:51]
	v_mfma_f32_16x16x32_bf16 v[36:39], v[174:177], v[204:207], v[36:39]
	v_mfma_f32_16x16x32_bf16 v[32:35], v[182:185], v[204:207], v[32:35]
	v_mfma_f32_16x16x32_bf16 v[20:23], v[174:177], v[212:215], v[20:23]
	v_mfma_f32_16x16x32_bf16 v[16:19], v[182:185], v[212:215], v[16:19]
	v_mfma_f32_16x16x32_bf16 v[4:7], v[174:177], v[220:223], v[4:7]
	v_mfma_f32_16x16x32_bf16 v[0:3], v[182:185], v[220:223], v[0:3]
	s_setprio 0
	s_barrier
	s_add_i32 s61, 0, 0x18000
	v_add_u32_e32 v165, s61, v159
	s_add_i32 s62, 0, 0x1c000
	ds_read_b128 v[128:131], v165
	ds_read_b128 v[132:135], v165 offset:1024
	ds_read_b128 v[152:155], v165 offset:2048
	ds_read_b128 v[166:169], v165 offset:3072
	v_add_u32_e32 v165, s62, v159
	ds_read_b128 v[170:173], v165
	ds_read_b128 v[174:177], v165 offset:1024
	ds_read_b128 v[178:181], v165 offset:2048
	ds_read_b128 v[182:185], v165 offset:3072
	s_add_u32 s8, s38, 0xb0000
	s_addc_u32 s9, s39, 0
	s_mov_b32 m0, s44
	v_lshl_add_u64 v[228:229], s[8:9], 0, v[136:137]
	ds_read_b128 v[192:195], v163 offset:32768
	ds_read_b128 v[196:199], v163 offset:33792
	ds_read_b128 v[200:203], v163 offset:34816
	ds_read_b128 v[204:207], v163 offset:35840
	ds_read_b128 v[208:211], v163 offset:36864
	ds_read_b128 v[212:215], v163 offset:37888
	ds_read_b128 v[216:219], v163 offset:38912
	ds_read_b128 v[220:223], v163 offset:39936
	global_load_lds_dwordx4 v[228:229], off
	v_lshl_add_u64 v[228:229], s[8:9], 0, v[140:141]
	s_mov_b32 m0, s45
	s_nop 0
	global_load_lds_dwordx4 v[228:229], off
	s_waitcnt vmcnt(8)
	s_waitcnt lgkmcnt(0)
	s_barrier
	s_setprio 1
	v_mfma_f32_16x16x32_bf16 v[124:127], v[128:131], v[192:195], v[124:127]
	v_mfma_f32_16x16x32_bf16 v[120:123], v[152:155], v[192:195], v[120:123]
	v_mfma_f32_16x16x32_bf16 v[108:111], v[128:131], v[200:203], v[108:111]
	v_mfma_f32_16x16x32_bf16 v[104:107], v[152:155], v[200:203], v[104:107]
	v_mfma_f32_16x16x32_bf16 v[92:95], v[128:131], v[208:211], v[92:95]
	v_mfma_f32_16x16x32_bf16 v[88:91], v[152:155], v[208:211], v[88:91]
	v_mfma_f32_16x16x32_bf16 v[76:79], v[128:131], v[216:219], v[76:79]
	v_mfma_f32_16x16x32_bf16 v[72:75], v[152:155], v[216:219], v[72:75]
	v_mfma_f32_16x16x32_bf16 v[124:127], v[132:135], v[196:199], v[124:127]
	v_mfma_f32_16x16x32_bf16 v[120:123], v[166:169], v[196:199], v[120:123]
	v_mfma_f32_16x16x32_bf16 v[108:111], v[132:135], v[204:207], v[108:111]
	v_mfma_f32_16x16x32_bf16 v[104:107], v[166:169], v[204:207], v[104:107]
	v_mfma_f32_16x16x32_bf16 v[92:95], v[132:135], v[212:215], v[92:95]
	v_mfma_f32_16x16x32_bf16 v[88:91], v[166:169], v[212:215], v[88:91]
	v_mfma_f32_16x16x32_bf16 v[76:79], v[132:135], v[220:223], v[76:79]
	v_mfma_f32_16x16x32_bf16 v[72:75], v[166:169], v[220:223], v[72:75]
	v_mfma_f32_16x16x32_bf16 v[116:119], v[170:173], v[192:195], v[116:119]
	v_mfma_f32_16x16x32_bf16 v[112:115], v[178:181], v[192:195], v[112:115]
	v_mfma_f32_16x16x32_bf16 v[100:103], v[170:173], v[200:203], v[100:103]
	v_mfma_f32_16x16x32_bf16 v[96:99], v[178:181], v[200:203], v[96:99]
	v_mfma_f32_16x16x32_bf16 v[84:87], v[170:173], v[208:211], v[84:87]
	v_mfma_f32_16x16x32_bf16 v[80:83], v[178:181], v[208:211], v[80:83]
	v_mfma_f32_16x16x32_bf16 v[68:71], v[170:173], v[216:219], v[68:71]
	v_mfma_f32_16x16x32_bf16 v[64:67], v[178:181], v[216:219], v[64:67]
	v_mfma_f32_16x16x32_bf16 v[116:119], v[174:177], v[196:199], v[116:119]
	v_mfma_f32_16x16x32_bf16 v[112:115], v[182:185], v[196:199], v[112:115]
	v_mfma_f32_16x16x32_bf16 v[100:103], v[174:177], v[204:207], v[100:103]
	v_mfma_f32_16x16x32_bf16 v[96:99], v[182:185], v[204:207], v[96:99]
	v_mfma_f32_16x16x32_bf16 v[84:87], v[174:177], v[212:215], v[84:87]
	v_mfma_f32_16x16x32_bf16 v[80:83], v[182:185], v[212:215], v[80:83]
	v_mfma_f32_16x16x32_bf16 v[68:71], v[174:177], v[220:223], v[68:71]
	v_mfma_f32_16x16x32_bf16 v[64:67], v[182:185], v[220:223], v[64:67]
	s_setprio 0
	s_barrier
; #define PG8_STAGE(bufoff, gbase, voff) do { _Pragma("unroll") for (int _i = 0; _i < 2; ++_i) \
;         __builtin_amdgcn_global_load_lds((const unsigned*)((const char*)(gbase) + (voff)[_i]), (PG8_LAS unsigned*)(lds + (bufoff) + ldsw + _i * 8192), 16, 0, 0); } while (0)
; #define PG8_LDA(dst, b, h) do { _Pragma("unroll") for (int m = 0; m < 4; ++m) _Pragma("unroll") for (int k = 0; k < 2; ++k) dst[m][k] = *(const PG8_LAS bf16x8*)(lds + PG8_SA(b, h) + aoff + m * 2048 + k * 1024); } while (0)
; #define PG8_MMA(ai, bj, At, Bt) do { __builtin_amdgcn_s_setprio(1); _Pragma("unroll") for (int m = 0; m < 4; ++m) _Pragma("unroll") for (int n = 0; n < 2; ++n) _Pragma("unroll") for (int k = 0; k < 2; ++k) \
;         acc[ai][bj][m][n] = __builtin_amdgcn_mfma_f32_16x16x32_bf16(Bt[n][k], At[m][k], acc[ai][bj][m][n], 0, 0, 0); __builtin_amdgcn_s_setprio(0); } while (0)
; #define PG8_WAIT_V(n) asm volatile("s_waitcnt vmcnt(" #n ")" ::: "memory")
; #define PG8_WAIT_L(n) asm volatile("s_waitcnt lgkmcnt(" #n ")" ::: "memory")
; #define PG8_BAR __builtin_amdgcn_s_barrier()
; #define PG8_SCHED __builtin_amdgcn_sched_barrier(0)
; template <class Epi, class Sched, bool ALIGN_EPI = false, bool SP2 = false>
; __device__ __forceinline__ void gemm_phase(PG8_LAS unsigned char* lds, const Gemm g, const Sched& S, const Epi& E) {
;     ...
;             PG8_LDA(At, 1, 1); PG8_STAGE(PG8_SB(1, 0), b3, voffB); PG8_STAGE(PG8_SB(1, 1), b3 + hstep, voffB); PG8_STAGE(PG8_SA(1, 0), a3, voffA);
;             PG8_WAIT_V(8); PG8_WAIT_L(0); PG8_BAR; PG8_MMA(1, 0, At, B0); PG8_MMA(1, 1, At, B1); PG8_BAR; PG8_SCHED;
	s_add_i32 s8, s61, s41
	v_lshl_add_u64 v[156:157], v[156:157], 0, s[14:15]
	s_mov_b32 m0, s8
	ds_read_b128 v[192:195], v163 offset:49152
	ds_read_b128 v[196:199], v163 offset:50176
	ds_read_b128 v[200:203], v163 offset:51200
	ds_read_b128 v[204:207], v163 offset:52224
	ds_read_b128 v[208:211], v163 offset:53248
	ds_read_b128 v[212:215], v163 offset:54272
	ds_read_b128 v[216:219], v163 offset:55296
	ds_read_b128 v[220:223], v163 offset:56320
	global_load_lds_dwordx4 v[156:157], off
	s_add_i32 m0, s8, 0x2000
	s_add_u32 s8, s36, 0xb0080
	v_lshl_add_u64 v[156:157], v[186:187], 0, s[14:15]
	s_addc_u32 s9, s37, 0
	s_add_i32 s36, s62, s41
	global_load_lds_dwordx4 v[156:157], off
	v_lshl_add_u64 v[156:157], s[8:9], 0, v[138:139]
	s_mov_b32 m0, s36
	s_nop 0
	global_load_lds_dwordx4 v[156:157], off
	v_lshl_add_u64 v[156:157], s[8:9], 0, v[142:143]
	s_add_i32 m0, s36, 0x2000
	s_nop 0
	global_load_lds_dwordx4 v[156:157], off
	v_lshl_add_u64 v[156:157], v[224:225], 0, s[14:15]
	s_mov_b32 m0, s47
	s_nop 0
	global_load_lds_dwordx4 v[156:157], off
	v_lshl_add_u64 v[156:157], v[226:227], 0, s[14:15]
	s_mov_b32 m0, s48
	s_nop 0
	global_load_lds_dwordx4 v[156:157], off
	s_waitcnt vmcnt(8)
	s_waitcnt lgkmcnt(0)
	s_barrier
	s_setprio 1
	v_mfma_f32_16x16x32_bf16 v[60:63], v[128:131], v[192:195], v[60:63]
	v_mfma_f32_16x16x32_bf16 v[56:59], v[152:155], v[192:195], v[56:59]
	v_mfma_f32_16x16x32_bf16 v[44:47], v[128:131], v[200:203], v[44:47]
	v_mfma_f32_16x16x32_bf16 v[40:43], v[152:155], v[200:203], v[40:43]
	v_mfma_f32_16x16x32_bf16 v[28:31], v[128:131], v[208:211], v[28:31]
	v_mfma_f32_16x16x32_bf16 v[24:27], v[152:155], v[208:211], v[24:27]
	v_mfma_f32_16x16x32_bf16 v[12:15], v[128:131], v[216:219], v[12:15]
	v_mfma_f32_16x16x32_bf16 v[8:11], v[152:155], v[216:219], v[8:11]
	v_mfma_f32_16x16x32_bf16 v[60:63], v[132:135], v[196:199], v[60:63]
	v_mfma_f32_16x16x32_bf16 v[56:59], v[166:169], v[196:199], v[56:59]
	v_mfma_f32_16x16x32_bf16 v[44:47], v[132:135], v[204:207], v[44:47]
	v_mfma_f32_16x16x32_bf16 v[40:43], v[166:169], v[204:207], v[40:43]
	v_mfma_f32_16x16x32_bf16 v[28:31], v[132:135], v[212:215], v[28:31]
	v_mfma_f32_16x16x32_bf16 v[24:27], v[166:169], v[212:215], v[24:27]
	v_mfma_f32_16x16x32_bf16 v[12:15], v[132:135], v[220:223], v[12:15]
	v_mfma_f32_16x16x32_bf16 v[8:11], v[166:169], v[220:223], v[8:11]
	v_mfma_f32_16x16x32_bf16 v[52:55], v[170:173], v[192:195], v[52:55]
	v_mfma_f32_16x16x32_bf16 v[48:51], v[178:181], v[192:195], v[48:51]
	v_mfma_f32_16x16x32_bf16 v[36:39], v[170:173], v[200:203], v[36:39]
	v_mfma_f32_16x16x32_bf16 v[32:35], v[178:181], v[200:203], v[32:35]
	v_mfma_f32_16x16x32_bf16 v[20:23], v[170:173], v[208:211], v[20:23]
	v_mfma_f32_16x16x32_bf16 v[16:19], v[178:181], v[208:211], v[16:19]
	v_mfma_f32_16x16x32_bf16 v[4:7], v[170:173], v[216:219], v[4:7]
	v_mfma_f32_16x16x32_bf16 v[0:3], v[178:181], v[216:219], v[0:3]
	v_mfma_f32_16x16x32_bf16 v[52:55], v[174:177], v[196:199], v[52:55]
	v_mfma_f32_16x16x32_bf16 v[48:51], v[182:185], v[196:199], v[48:51]
	v_mfma_f32_16x16x32_bf16 v[36:39], v[174:177], v[204:207], v[36:39]
	v_mfma_f32_16x16x32_bf16 v[32:35], v[182:185], v[204:207], v[32:35]
	v_mfma_f32_16x16x32_bf16 v[20:23], v[174:177], v[212:215], v[20:23]
	v_mfma_f32_16x16x32_bf16 v[16:19], v[182:185], v[212:215], v[16:19]
	v_mfma_f32_16x16x32_bf16 v[4:7], v[174:177], v[220:223], v[4:7]
	v_mfma_f32_16x16x32_bf16 v[0:3], v[182:185], v[220:223], v[0:3]
	s_setprio 0
	s_barrier
	s_add_i32 s60, s60, 2
	s_add_u32 s58, s58, 0x100
	s_addc_u32 s59, s59, 0
	s_mov_b64 s[8:9], s[34:35]
	.p2alignl 6, 3212836864

; #define PG8_STAGE(bufoff, gbase, voff) do { _Pragma("unroll") for (int _i = 0; _i < 2; ++_i) \
;         __builtin_amdgcn_global_load_lds((const unsigned*)((const char*)(gbase) + (voff)[_i]), (PG8_LAS unsigned*)(lds + (bufoff) + ldsw + _i * 8192), 16, 0, 0); } while (0)
; #define PG8_LDA(dst, b, h) do { _Pragma("unroll") for (int m = 0; m < 4; ++m) _Pragma("unroll") for (int k = 0; k < 2; ++k) dst[m][k] = *(const PG8_LAS bf16x8*)(lds + PG8_SA(b, h) + aoff + m * 2048 + k * 1024); } while (0)
; #define PG8_LDB(dst, b, h) do { _Pragma("unroll") for (int n = 0; n < 2; ++n) _Pragma("unroll") for (int k = 0; k < 2; ++k) dst[n][k] = *(const PG8_LAS bf16x8*)(lds + PG8_SB(b, h) + boff + n * 2048 + k * 1024); } while (0)
; #define PG8_WAIT_V(n) asm volatile("s_waitcnt vmcnt(" #n ")" ::: "memory")
; #define PG8_WAIT_L(n) asm volatile("s_waitcnt lgkmcnt(" #n ")" ::: "memory")
; #define PG8_BAR __builtin_amdgcn_s_barrier()
; #define PG8_SCHED __builtin_amdgcn_sched_barrier(0)
; template <class Epi, class Sched, bool ALIGN_EPI = false, bool SP2 = false>
; __device__ __forceinline__ void gemm_phase(PG8_LAS unsigned char* lds, const Gemm g, const Sched& S, const Epi& E) {
;     ...
;         const bool has_next = S.next(ui + 1, nxt);
;         const char* nA = has_next ? (const char*)g.A + (size_t)nxt.pm * tstep : cA; const char* nB = has_next ? (const char*)g.Bt + (size_t)nxt.pn * tstep : cB;
;         for (int t = 0; t < nt; t += 2) {
;             const bool last = (t == nt - 2);
;             const char* a1 = cA + (size_t)(t + 1) * kstep;
;             const char* a2 = last ? nA : cA + (size_t)(t + 2) * kstep; const char* b2 = last ? nB : cB + (size_t)(t + 2) * kstep;
;             const char* a3 = a2 + kstep; const char* b3 = b2 + kstep;
;             if (last && has_next) S.a_ready(nxt);
;             if constexpr (SP2) {
;             PG8_LDB(B0, 0, 0); PG8_LDB(B1, 0, 1); PG8_SCHED; PG8_LDA(At, 0, 0); PG8_STAGE(PG8_SA(1, 1), a1 + hstep, voffA);
;             PG8_WAIT_V(8); PG8_WAIT_L(0); PG8_BAR; PG8_MMA(0, 0, At, B0); PG8_MMA(0, 1, At, B1); PG8_BAR; PG8_SCHED;
;             PG8_LDA(At, 0, 1); PG8_STAGE(PG8_SB(0, 0), b2, voffB); PG8_STAGE(PG8_SB(0, 1), b2 + hstep, voffB); PG8_STAGE(PG8_SA(0, 0), a2, voffA);
;             PG8_WAIT_V(8); PG8_WAIT_L(0); PG8_BAR; PG8_MMA(1, 0, At, B0); PG8_MMA(1, 1, At, B1); PG8_BAR; PG8_SCHED;
.LBB0_373:
	s_ashr_i32 s31, s30, 31
	s_lshl_b64 s[34:35], s[30:31], 19
	v_readlane_b32 s36, v235, 31
	v_readlane_b32 s37, v235, 32
	s_add_u32 s34, s36, s34
	s_addc_u32 s35, s37, s35
	s_and_b64 s[36:37], s[6:7], exec
	s_cselect_b32 s1, s35, s3
	s_cselect_b32 s25, s34, s2
	s_ashr_i32 s29, s28, 31
	s_lshl_b64 s[36:37], s[28:29], 19
	s_add_u32 s36, s10, s36
	s_addc_u32 s37, s11, s37
	s_and_b64 s[40:41], s[6:7], exec
	s_cselect_b32 s29, s37, s39
	s_cselect_b32 s31, s36, s38
	s_add_u32 s2, s2, 0x40080
	s_addc_u32 s3, s3, 0
	s_add_u32 s58, s38, 0x100
	s_addc_u32 s59, s39, 0
	s_mov_b32 s60, -2
	ds_read_b128 v[128:131], v171
	ds_read_b128 v[132:135], v171 offset:1024
	ds_read_b128 v[136:139], v171 offset:2048
	ds_read_b128 v[140:143], v171 offset:3072
	ds_read_b128 v[164:167], v172
	ds_read_b128 v[178:181], v172 offset:1024
	ds_read_b128 v[182:185], v172 offset:2048
	ds_read_b128 v[192:195], v172 offset:3072
	s_add_u32 s38, s2, 0xfffc0080
	s_addc_u32 s39, s3, -1
	s_cmp_eq_u32 s60, 12
	s_cselect_b32 s41, s1, s39
	s_cselect_b32 s40, s25, s38
	s_cselect_b32 s39, s29, s59
	s_cselect_b32 s38, s31, s58
	v_lshl_add_u64 v[168:169], s[2:3], 0, v[156:157]
	s_add_i32 m0, s44, 0xc000
	ds_read_b128 v[196:199], v173
	ds_read_b128 v[200:203], v173 offset:1024
	ds_read_b128 v[204:207], v173 offset:2048
	ds_read_b128 v[208:211], v173 offset:3072
	ds_read_b128 v[212:215], v173 offset:4096
	ds_read_b128 v[216:219], v173 offset:5120
	ds_read_b128 v[220:223], v173 offset:6144
	ds_read_b128 v[224:227], v173 offset:7168
	global_load_lds_dwordx4 v[168:169], off
	v_lshl_add_u64 v[168:169], s[2:3], 0, v[158:159]
	s_add_i32 m0, s44, 0xe000
	s_nop 0
	global_load_lds_dwordx4 v[168:169], off
	s_waitcnt vmcnt(8)
	s_waitcnt lgkmcnt(0)
	s_barrier
	s_setprio 1
	v_mfma_f32_16x16x32_bf16 v[124:127], v[128:131], v[196:199], 0
	v_mfma_f32_16x16x32_bf16 v[120:123], v[136:139], v[196:199], 0
	v_mfma_f32_16x16x32_bf16 v[108:111], v[128:131], v[204:207], 0
	v_mfma_f32_16x16x32_bf16 v[104:107], v[136:139], v[204:207], 0
	v_mfma_f32_16x16x32_bf16 v[92:95], v[128:131], v[212:215], 0
	v_mfma_f32_16x16x32_bf16 v[88:91], v[136:139], v[212:215], 0
	v_mfma_f32_16x16x32_bf16 v[76:79], v[128:131], v[220:223], 0
	v_mfma_f32_16x16x32_bf16 v[72:75], v[136:139], v[220:223], 0
	v_mfma_f32_16x16x32_bf16 v[124:127], v[132:135], v[200:203], v[124:127]
	v_mfma_f32_16x16x32_bf16 v[120:123], v[140:143], v[200:203], v[120:123]
	v_mfma_f32_16x16x32_bf16 v[108:111], v[132:135], v[208:211], v[108:111]
	v_mfma_f32_16x16x32_bf16 v[104:107], v[140:143], v[208:211], v[104:107]
	v_mfma_f32_16x16x32_bf16 v[92:95], v[132:135], v[216:219], v[92:95]
	v_mfma_f32_16x16x32_bf16 v[88:91], v[140:143], v[216:219], v[88:91]
	v_mfma_f32_16x16x32_bf16 v[76:79], v[132:135], v[224:227], v[76:79]
	v_mfma_f32_16x16x32_bf16 v[72:75], v[140:143], v[224:227], v[72:75]
	v_mfma_f32_16x16x32_bf16 v[116:119], v[164:167], v[196:199], 0
	v_mfma_f32_16x16x32_bf16 v[112:115], v[182:185], v[196:199], 0
	v_mfma_f32_16x16x32_bf16 v[100:103], v[164:167], v[204:207], 0
	v_mfma_f32_16x16x32_bf16 v[96:99], v[182:185], v[204:207], 0
	v_mfma_f32_16x16x32_bf16 v[84:87], v[164:167], v[212:215], 0
	v_mfma_f32_16x16x32_bf16 v[80:83], v[182:185], v[212:215], 0
	v_mfma_f32_16x16x32_bf16 v[68:71], v[164:167], v[220:223], 0
	v_mfma_f32_16x16x32_bf16 v[64:67], v[182:185], v[220:223], 0
	v_mfma_f32_16x16x32_bf16 v[116:119], v[178:181], v[200:203], v[116:119]
	v_mfma_f32_16x16x32_bf16 v[112:115], v[192:195], v[200:203], v[112:115]
	v_mfma_f32_16x16x32_bf16 v[100:103], v[178:181], v[208:211], v[100:103]
	v_mfma_f32_16x16x32_bf16 v[96:99], v[192:195], v[208:211], v[96:99]
	v_mfma_f32_16x16x32_bf16 v[84:87], v[178:181], v[216:219], v[84:87]
	v_mfma_f32_16x16x32_bf16 v[80:83], v[192:195], v[216:219], v[80:83]
	v_mfma_f32_16x16x32_bf16 v[68:71], v[178:181], v[224:227], v[68:71]
	v_mfma_f32_16x16x32_bf16 v[64:67], v[192:195], v[224:227], v[64:67]
	s_setprio 0
	s_barrier
	s_add_i32 s61, s52, s33
	v_lshl_add_u64 v[168:169], s[38:39], 0, v[148:149]
	s_mov_b32 m0, s61
	ds_read_b128 v[196:199], v173 offset:16384
	ds_read_b128 v[200:203], v173 offset:17408
	ds_read_b128 v[204:207], v173 offset:18432
	ds_read_b128 v[208:211], v173 offset:19456
	ds_read_b128 v[212:215], v173 offset:20480
	ds_read_b128 v[216:219], v173 offset:21504
	ds_read_b128 v[220:223], v173 offset:22528
	ds_read_b128 v[224:227], v173 offset:23552
	global_load_lds_dwordx4 v[168:169], off
	s_add_i32 m0, s61, 0x2000
	s_add_u32 s62, s38, 0x40000
	v_lshl_add_u64 v[186:187], s[38:39], 0, v[144:145]
	s_addc_u32 s63, s39, 0
	s_add_i32 s61, s53, s33
	global_load_lds_dwordx4 v[186:187], off
	v_lshl_add_u64 v[228:229], s[62:63], 0, v[148:149]
	s_mov_b32 m0, s61
	v_lshl_add_u64 v[230:231], s[40:41], 0, v[146:147]
	global_load_lds_dwordx4 v[228:229], off
	v_lshl_add_u64 v[228:229], s[62:63], 0, v[144:145]
	s_add_i32 m0, s61, 0x2000
	s_nop 0
	global_load_lds_dwordx4 v[228:229], off
	v_lshl_add_u64 v[228:229], s[40:41], 0, v[150:151]
	s_mov_b32 m0, s44
	s_nop 0
	global_load_lds_dwordx4 v[228:229], off
	s_mov_b32 m0, s45
	s_nop 0
	global_load_lds_dwordx4 v[230:231], off
	s_waitcnt vmcnt(8)
	s_waitcnt lgkmcnt(0)
	s_barrier
; #define PG8_STAGE(bufoff, gbase, voff) do { _Pragma("unroll") for (int _i = 0; _i < 2; ++_i) \
;         __builtin_amdgcn_global_load_lds((const unsigned*)((const char*)(gbase) + (voff)[_i]), (PG8_LAS unsigned*)(lds + (bufoff) + ldsw + _i * 8192), 16, 0, 0); } while (0)
; #define PG8_LDA(dst, b, h) do { _Pragma("unroll") for (int m = 0; m < 4; ++m) _Pragma("unroll") for (int k = 0; k < 2; ++k) dst[m][k] = *(const PG8_LAS bf16x8*)(lds + PG8_SA(b, h) + aoff + m * 2048 + k * 1024); } while (0)
; #define PG8_LDB(dst, b, h) do { _Pragma("unroll") for (int n = 0; n < 2; ++n) _Pragma("unroll") for (int k = 0; k < 2; ++k) dst[n][k] = *(const PG8_LAS bf16x8*)(lds + PG8_SB(b, h) + boff + n * 2048 + k * 1024); } while (0)
; #define PG8_MMA(ai, bj, At, Bt) do { __builtin_amdgcn_s_setprio(1); _Pragma("unroll") for (int m = 0; m < 4; ++m) _Pragma("unroll") for (int n = 0; n < 2; ++n) _Pragma("unroll") for (int k = 0; k < 2; ++k) \
;         acc[ai][bj][m][n] = __builtin_amdgcn_mfma_f32_16x16x32_bf16(Bt[n][k], At[m][k], acc[ai][bj][m][n], 0, 0, 0); __builtin_amdgcn_s_setprio(0); } while (0)
; #define PG8_WAIT_V(n) asm volatile("s_waitcnt vmcnt(" #n ")" ::: "memory")
; #define PG8_WAIT_L(n) asm volatile("s_waitcnt lgkmcnt(" #n ")" ::: "memory")
; #define PG8_BAR __builtin_amdgcn_s_barrier()
; #define PG8_SCHED __builtin_amdgcn_sched_barrier(0)
; template <class Epi, class Sched, bool ALIGN_EPI = false, bool SP2 = false>
; __device__ __forceinline__ void gemm_phase(PG8_LAS unsigned char* lds, const Gemm g, const Sched& S, const Epi& E) {
;     ...
;             PG8_WAIT_V(8); PG8_WAIT_L(0); PG8_BAR; PG8_MMA(1, 0, At, B0); PG8_MMA(1, 1, At, B1); PG8_BAR; PG8_SCHED;
;             PG8_LDB(B0, 1, 0); PG8_LDB(B1, 1, 1); PG8_SCHED; PG8_LDA(At, 1, 0); PG8_STAGE(PG8_SA(0, 1), a2 + hstep, voffA);
;             PG8_WAIT_V(8); PG8_WAIT_L(0); PG8_BAR; PG8_MMA(0, 0, At, B0); PG8_MMA(0, 1, At, B1); PG8_BAR; PG8_SCHED;
	s_setprio 1
	v_mfma_f32_16x16x32_bf16 v[60:63], v[128:131], v[196:199], 0
	v_mfma_f32_16x16x32_bf16 v[56:59], v[136:139], v[196:199], 0
	v_mfma_f32_16x16x32_bf16 v[44:47], v[128:131], v[204:207], 0
	v_mfma_f32_16x16x32_bf16 v[40:43], v[136:139], v[204:207], 0
	v_mfma_f32_16x16x32_bf16 v[28:31], v[128:131], v[212:215], 0
	v_mfma_f32_16x16x32_bf16 v[24:27], v[136:139], v[212:215], 0
	v_mfma_f32_16x16x32_bf16 v[12:15], v[128:131], v[220:223], 0
	v_mfma_f32_16x16x32_bf16 v[8:11], v[136:139], v[220:223], 0
	v_mfma_f32_16x16x32_bf16 v[60:63], v[132:135], v[200:203], v[60:63]
	v_mfma_f32_16x16x32_bf16 v[56:59], v[140:143], v[200:203], v[56:59]
	v_mfma_f32_16x16x32_bf16 v[44:47], v[132:135], v[208:211], v[44:47]
	v_mfma_f32_16x16x32_bf16 v[40:43], v[140:143], v[208:211], v[40:43]
	v_mfma_f32_16x16x32_bf16 v[28:31], v[132:135], v[216:219], v[28:31]
	v_mfma_f32_16x16x32_bf16 v[24:27], v[140:143], v[216:219], v[24:27]
	v_mfma_f32_16x16x32_bf16 v[12:15], v[132:135], v[224:227], v[12:15]
	v_mfma_f32_16x16x32_bf16 v[8:11], v[140:143], v[224:227], v[8:11]
	v_mfma_f32_16x16x32_bf16 v[52:55], v[164:167], v[196:199], 0
	v_mfma_f32_16x16x32_bf16 v[48:51], v[182:185], v[196:199], 0
	v_mfma_f32_16x16x32_bf16 v[36:39], v[164:167], v[204:207], 0
	v_mfma_f32_16x16x32_bf16 v[32:35], v[182:185], v[204:207], 0
	v_mfma_f32_16x16x32_bf16 v[20:23], v[164:167], v[212:215], 0
	v_mfma_f32_16x16x32_bf16 v[16:19], v[182:185], v[212:215], 0
	v_mfma_f32_16x16x32_bf16 v[4:7], v[164:167], v[220:223], 0
	v_mfma_f32_16x16x32_bf16 v[0:3], v[182:185], v[220:223], 0
	v_mfma_f32_16x16x32_bf16 v[52:55], v[178:181], v[200:203], v[52:55]
	v_mfma_f32_16x16x32_bf16 v[48:51], v[192:195], v[200:203], v[48:51]
	v_mfma_f32_16x16x32_bf16 v[36:39], v[178:181], v[208:211], v[36:39]
	v_mfma_f32_16x16x32_bf16 v[32:35], v[192:195], v[208:211], v[32:35]
	v_mfma_f32_16x16x32_bf16 v[20:23], v[178:181], v[216:219], v[20:23]
	v_mfma_f32_16x16x32_bf16 v[16:19], v[192:195], v[216:219], v[16:19]
	v_mfma_f32_16x16x32_bf16 v[4:7], v[178:181], v[224:227], v[4:7]
	v_mfma_f32_16x16x32_bf16 v[0:3], v[192:195], v[224:227], v[0:3]
	s_setprio 0
	s_barrier
	s_add_i32 s61, 0, 0x18000
	s_add_i32 s62, 0, 0x1c000
	v_add_u32_e32 v140, s61, v170
	v_add_u32_e32 v152, s62, v170
	ds_read_b128 v[128:131], v140
	ds_read_b128 v[132:135], v140 offset:1024
	ds_read_b128 v[136:139], v140 offset:2048
	ds_read_b128 v[140:143], v140 offset:3072
	ds_read_b128 v[164:167], v152
	ds_read_b128 v[178:181], v152 offset:1024
	ds_read_b128 v[182:185], v152 offset:2048
	ds_read_b128 v[192:195], v152 offset:3072
	s_add_u32 s40, s40, 0x40000
	s_addc_u32 s41, s41, 0
	s_mov_b32 m0, s46
	v_lshl_add_u64 v[232:233], s[40:41], 0, v[150:151]
	ds_read_b128 v[196:199], v173 offset:32768
	ds_read_b128 v[200:203], v173 offset:33792
	ds_read_b128 v[204:207], v173 offset:34816
	ds_read_b128 v[208:211], v173 offset:35840
	ds_read_b128 v[212:215], v173 offset:36864
	ds_read_b128 v[216:219], v173 offset:37888
	ds_read_b128 v[220:223], v173 offset:38912
	ds_read_b128 v[224:227], v173 offset:39936
	global_load_lds_dwordx4 v[232:233], off
	v_lshl_add_u64 v[232:233], s[40:41], 0, v[146:147]
	s_mov_b32 m0, s47
	s_nop 0
	global_load_lds_dwordx4 v[232:233], off
	s_waitcnt vmcnt(8)
	s_waitcnt lgkmcnt(0)
	s_barrier
	s_setprio 1
	v_mfma_f32_16x16x32_bf16 v[124:127], v[128:131], v[196:199], v[124:127]
	v_mfma_f32_16x16x32_bf16 v[120:123], v[136:139], v[196:199], v[120:123]
	v_mfma_f32_16x16x32_bf16 v[108:111], v[128:131], v[204:207], v[108:111]
	v_mfma_f32_16x16x32_bf16 v[104:107], v[136:139], v[204:207], v[104:107]
	v_mfma_f32_16x16x32_bf16 v[92:95], v[128:131], v[212:215], v[92:95]
	v_mfma_f32_16x16x32_bf16 v[88:91], v[136:139], v[212:215], v[88:91]
	v_mfma_f32_16x16x32_bf16 v[76:79], v[128:131], v[220:223], v[76:79]
	v_mfma_f32_16x16x32_bf16 v[72:75], v[136:139], v[220:223], v[72:75]
	v_mfma_f32_16x16x32_bf16 v[124:127], v[132:135], v[200:203], v[124:127]
	v_mfma_f32_16x16x32_bf16 v[120:123], v[140:143], v[200:203], v[120:123]
	v_mfma_f32_16x16x32_bf16 v[108:111], v[132:135], v[208:211], v[108:111]
	v_mfma_f32_16x16x32_bf16 v[104:107], v[140:143], v[208:211], v[104:107]
	v_mfma_f32_16x16x32_bf16 v[92:95], v[132:135], v[216:219], v[92:95]
	v_mfma_f32_16x16x32_bf16 v[88:91], v[140:143], v[216:219], v[88:91]
	v_mfma_f32_16x16x32_bf16 v[76:79], v[132:135], v[224:227], v[76:79]
	v_mfma_f32_16x16x32_bf16 v[72:75], v[140:143], v[224:227], v[72:75]
	v_mfma_f32_16x16x32_bf16 v[116:119], v[164:167], v[196:199], v[116:119]
	v_mfma_f32_16x16x32_bf16 v[112:115], v[182:185], v[196:199], v[112:115]
	v_mfma_f32_16x16x32_bf16 v[100:103], v[164:167], v[204:207], v[100:103]
	v_mfma_f32_16x16x32_bf16 v[96:99], v[182:185], v[204:207], v[96:99]
	v_mfma_f32_16x16x32_bf16 v[84:87], v[164:167], v[212:215], v[84:87]
	v_mfma_f32_16x16x32_bf16 v[80:83], v[182:185], v[212:215], v[80:83]
	v_mfma_f32_16x16x32_bf16 v[68:71], v[164:167], v[220:223], v[68:71]
	v_mfma_f32_16x16x32_bf16 v[64:67], v[182:185], v[220:223], v[64:67]
	v_mfma_f32_16x16x32_bf16 v[116:119], v[178:181], v[200:203], v[116:119]
	v_mfma_f32_16x16x32_bf16 v[112:115], v[192:195], v[200:203], v[112:115]
	v_mfma_f32_16x16x32_bf16 v[100:103], v[178:181], v[208:211], v[100:103]
	v_mfma_f32_16x16x32_bf16 v[96:99], v[192:195], v[208:211], v[96:99]
	v_mfma_f32_16x16x32_bf16 v[84:87], v[178:181], v[216:219], v[84:87]
	v_mfma_f32_16x16x32_bf16 v[80:83], v[192:195], v[216:219], v[80:83]
	v_mfma_f32_16x16x32_bf16 v[68:71], v[178:181], v[224:227], v[68:71]
	v_mfma_f32_16x16x32_bf16 v[64:67], v[192:195], v[224:227], v[64:67]
	s_setprio 0
	s_barrier
; #define PG8_STAGE(bufoff, gbase, voff) do { _Pragma("unroll") for (int _i = 0; _i < 2; ++_i) \
;         __builtin_amdgcn_global_load_lds((const unsigned*)((const char*)(gbase) + (voff)[_i]), (PG8_LAS unsigned*)(lds + (bufoff) + ldsw + _i * 8192), 16, 0, 0); } while (0)
; #define PG8_LDA(dst, b, h) do { _Pragma("unroll") for (int m = 0; m < 4; ++m) _Pragma("unroll") for (int k = 0; k < 2; ++k) dst[m][k] = *(const PG8_LAS bf16x8*)(lds + PG8_SA(b, h) + aoff + m * 2048 + k * 1024); } while (0)
; #define PG8_MMA(ai, bj, At, Bt) do { __builtin_amdgcn_s_setprio(1); _Pragma("unroll") for (int m = 0; m < 4; ++m) _Pragma("unroll") for (int n = 0; n < 2; ++n) _Pragma("unroll") for (int k = 0; k < 2; ++k) \
;         acc[ai][bj][m][n] = __builtin_amdgcn_mfma_f32_16x16x32_bf16(Bt[n][k], At[m][k], acc[ai][bj][m][n], 0, 0, 0); __builtin_amdgcn_s_setprio(0); } while (0)
; #define PG8_WAIT_V(n) asm volatile("s_waitcnt vmcnt(" #n ")" ::: "memory")
; #define PG8_WAIT_L(n) asm volatile("s_waitcnt lgkmcnt(" #n ")" ::: "memory")
; #define PG8_BAR __builtin_amdgcn_s_barrier()
; #define PG8_SCHED __builtin_amdgcn_sched_barrier(0)
; template <class Epi, class Sched, bool ALIGN_EPI = false, bool SP2 = false>
; __device__ __forceinline__ void gemm_phase(PG8_LAS unsigned char* lds, const Gemm g, const Sched& S, const Epi& E) {
;     ...
;             PG8_LDA(At, 1, 1); PG8_STAGE(PG8_SB(1, 0), b3, voffB); PG8_STAGE(PG8_SB(1, 1), b3 + hstep, voffB); PG8_STAGE(PG8_SA(1, 0), a3, voffA);
;             PG8_WAIT_V(8); PG8_WAIT_L(0); PG8_BAR; PG8_MMA(1, 0, At, B0); PG8_MMA(1, 1, At, B1); PG8_BAR; PG8_SCHED;
	s_add_i32 s40, s61, s33
	v_lshl_add_u64 v[168:169], v[168:169], 0, s[16:17]
	s_mov_b32 m0, s40
	ds_read_b128 v[196:199], v173 offset:49152
	ds_read_b128 v[200:203], v173 offset:50176
	ds_read_b128 v[204:207], v173 offset:51200
	ds_read_b128 v[208:211], v173 offset:52224
	ds_read_b128 v[212:215], v173 offset:53248
	ds_read_b128 v[216:219], v173 offset:54272
	ds_read_b128 v[220:223], v173 offset:55296
	ds_read_b128 v[224:227], v173 offset:56320
	global_load_lds_dwordx4 v[168:169], off
	s_add_i32 m0, s40, 0x2000
	s_add_u32 s38, s38, 0x40080
	v_lshl_add_u64 v[168:169], v[186:187], 0, s[16:17]
	s_addc_u32 s39, s39, 0
	s_add_i32 s40, s62, s33
	global_load_lds_dwordx4 v[168:169], off
	v_lshl_add_u64 v[168:169], s[38:39], 0, v[148:149]
	s_mov_b32 m0, s40
	s_nop 0
	global_load_lds_dwordx4 v[168:169], off
	v_lshl_add_u64 v[168:169], s[38:39], 0, v[144:145]
	s_add_i32 m0, s40, 0x2000
	s_nop 0
	global_load_lds_dwordx4 v[168:169], off
	v_lshl_add_u64 v[168:169], v[228:229], 0, s[16:17]
	s_mov_b32 m0, s48
	s_nop 0
	global_load_lds_dwordx4 v[168:169], off
	v_lshl_add_u64 v[168:169], v[230:231], 0, s[16:17]
	s_mov_b32 m0, s49
	s_nop 0
	global_load_lds_dwordx4 v[168:169], off
	s_waitcnt vmcnt(8)
	s_waitcnt lgkmcnt(0)
	s_barrier
	s_setprio 1
	v_mfma_f32_16x16x32_bf16 v[60:63], v[128:131], v[196:199], v[60:63]
	v_mfma_f32_16x16x32_bf16 v[56:59], v[136:139], v[196:199], v[56:59]
	v_mfma_f32_16x16x32_bf16 v[44:47], v[128:131], v[204:207], v[44:47]
	v_mfma_f32_16x16x32_bf16 v[40:43], v[136:139], v[204:207], v[40:43]
	v_mfma_f32_16x16x32_bf16 v[28:31], v[128:131], v[212:215], v[28:31]
	v_mfma_f32_16x16x32_bf16 v[24:27], v[136:139], v[212:215], v[24:27]
	v_mfma_f32_16x16x32_bf16 v[12:15], v[128:131], v[220:223], v[12:15]
	v_mfma_f32_16x16x32_bf16 v[8:11], v[136:139], v[220:223], v[8:11]
	v_mfma_f32_16x16x32_bf16 v[60:63], v[132:135], v[200:203], v[60:63]
	v_mfma_f32_16x16x32_bf16 v[56:59], v[140:143], v[200:203], v[56:59]
	v_mfma_f32_16x16x32_bf16 v[44:47], v[132:135], v[208:211], v[44:47]
	v_mfma_f32_16x16x32_bf16 v[40:43], v[140:143], v[208:211], v[40:43]
	v_mfma_f32_16x16x32_bf16 v[28:31], v[132:135], v[216:219], v[28:31]
	v_mfma_f32_16x16x32_bf16 v[24:27], v[140:143], v[216:219], v[24:27]
	v_mfma_f32_16x16x32_bf16 v[12:15], v[132:135], v[224:227], v[12:15]
	v_mfma_f32_16x16x32_bf16 v[8:11], v[140:143], v[224:227], v[8:11]
	v_mfma_f32_16x16x32_bf16 v[52:55], v[164:167], v[196:199], v[52:55]
	v_mfma_f32_16x16x32_bf16 v[48:51], v[182:185], v[196:199], v[48:51]
	v_mfma_f32_16x16x32_bf16 v[36:39], v[164:167], v[204:207], v[36:39]
	v_mfma_f32_16x16x32_bf16 v[32:35], v[182:185], v[204:207], v[32:35]
	v_mfma_f32_16x16x32_bf16 v[20:23], v[164:167], v[212:215], v[20:23]
	v_mfma_f32_16x16x32_bf16 v[16:19], v[182:185], v[212:215], v[16:19]
	v_mfma_f32_16x16x32_bf16 v[4:7], v[164:167], v[220:223], v[4:7]
	v_mfma_f32_16x16x32_bf16 v[0:3], v[182:185], v[220:223], v[0:3]
	v_mfma_f32_16x16x32_bf16 v[52:55], v[178:181], v[200:203], v[52:55]
	v_mfma_f32_16x16x32_bf16 v[48:51], v[192:195], v[200:203], v[48:51]
	v_mfma_f32_16x16x32_bf16 v[36:39], v[178:181], v[208:211], v[36:39]
	v_mfma_f32_16x16x32_bf16 v[32:35], v[192:195], v[208:211], v[32:35]
	v_mfma_f32_16x16x32_bf16 v[20:23], v[178:181], v[216:219], v[20:23]
	v_mfma_f32_16x16x32_bf16 v[16:19], v[192:195], v[216:219], v[16:19]
	v_mfma_f32_16x16x32_bf16 v[4:7], v[178:181], v[224:227], v[4:7]
	v_mfma_f32_16x16x32_bf16 v[0:3], v[192:195], v[224:227], v[0:3]
	s_setprio 0
	s_barrier
	s_add_i32 s60, s60, 2
	s_add_u32 s2, s2, 0x100
	s_addc_u32 s3, s3, 0
	s_add_u32 s58, s58, 0x100
	s_addc_u32 s59, s59, 0
	.p2alignl 6, 3212836864

; #define PG8_STAGE(bufoff, gbase, voff) do { _Pragma("unroll") for (int _i = 0; _i < 2; ++_i) \
;         __builtin_amdgcn_global_load_lds((const unsigned*)((const char*)(gbase) + (voff)[_i]), (PG8_LAS unsigned*)(lds + (bufoff) + ldsw + _i * 8192), 16, 0, 0); } while (0)
; #define PG8_LDA(dst, b, h) do { _Pragma("unroll") for (int m = 0; m < 4; ++m) _Pragma("unroll") for (int k = 0; k < 2; ++k) dst[m][k] = *(const PG8_LAS bf16x8*)(lds + PG8_SA(b, h) + aoff + m * 2048 + k * 1024); } while (0)
; #define PG8_LDB(dst, b, h) do { _Pragma("unroll") for (int n = 0; n < 2; ++n) _Pragma("unroll") for (int k = 0; k < 2; ++k) dst[n][k] = *(const PG8_LAS bf16x8*)(lds + PG8_SB(b, h) + boff + n * 2048 + k * 1024); } while (0)
; #define PG8_WAIT_V(n) asm volatile("s_waitcnt vmcnt(" #n ")" ::: "memory")
; #define PG8_WAIT_L(n) asm volatile("s_waitcnt lgkmcnt(" #n ")" ::: "memory")
; #define PG8_BAR __builtin_amdgcn_s_barrier()
; #define PG8_SCHED __builtin_amdgcn_sched_barrier(0)
; template <class Epi, class Sched, bool ALIGN_EPI = false, bool SP2 = false>
; __device__ __forceinline__ void gemm_phase(PG8_LAS unsigned char* lds, const Gemm g, const Sched& S, const Epi& E) {
;     ...
;         const bool has_next = S.next(ui + 1, nxt);
;         const char* nA = has_next ? (const char*)g.A + (size_t)nxt.pm * tstep : cA; const char* nB = has_next ? (const char*)g.Bt + (size_t)nxt.pn * tstep : cB;
;         for (int t = 0; t < nt; t += 2) {
;             const bool last = (t == nt - 2);
;             const char* a1 = cA + (size_t)(t + 1) * kstep;
;             const char* a2 = last ? nA : cA + (size_t)(t + 2) * kstep; const char* b2 = last ? nB : cB + (size_t)(t + 2) * kstep;
;             const char* a3 = a2 + kstep; const char* b3 = b2 + kstep;
;             if (last && has_next) S.a_ready(nxt);
;             if constexpr (SP2) {
;             PG8_LDB(B0, 0, 0); PG8_LDB(B1, 0, 1); PG8_SCHED; PG8_LDA(At, 0, 0); PG8_STAGE(PG8_SA(1, 1), a1 + hstep, voffA);
;             PG8_WAIT_V(8); PG8_WAIT_L(0); PG8_BAR; PG8_MMA(0, 0, At, B0); PG8_MMA(0, 1, At, B1); PG8_BAR; PG8_SCHED;
;             PG8_LDA(At, 0, 1); PG8_STAGE(PG8_SB(0, 0), b2, voffB); PG8_STAGE(PG8_SB(0, 1), b2 + hstep, voffB); PG8_STAGE(PG8_SA(0, 0), a2, voffA);
;             PG8_WAIT_V(8); PG8_WAIT_L(0); PG8_BAR; PG8_MMA(1, 0, At, B0); PG8_MMA(1, 1, At, B1); PG8_BAR; PG8_SCHED;
.LBB0_697:
	s_ashr_i32 s17, s16, 31
	s_lshl_b64 s[18:19], s[16:17], 19
	v_readlane_b32 s48, v235, 2
	v_readlane_b32 s49, v235, 3
	s_add_u32 s18, s48, s18
	s_addc_u32 s19, s49, s19
	s_and_b64 s[20:21], s[6:7], exec
	s_cselect_b32 s17, s19, s27
	s_cselect_b32 s23, s18, s26
	s_ashr_i32 s15, s14, 31
	s_lshl_b64 s[20:21], s[14:15], 19
	s_add_u32 s20, s33, s20
	s_addc_u32 s21, s34, s21
	s_and_b64 s[30:31], s[6:7], exec
	s_cselect_b32 s15, s21, s29
	s_cselect_b32 s47, s20, s28
	s_add_u32 s26, s26, 0x40080
	s_addc_u32 s27, s27, 0
	v_readlane_b32 s50, v235, 4
	s_add_u32 s48, s28, 0x100
	s_addc_u32 s49, s29, 0
	s_mov_b32 s50, -2
	s_waitcnt lgkmcnt(0)
	v_readlane_b32 s51, v235, 5
	ds_read_b128 v[144:147], v151
	ds_read_b128 v[156:159], v151 offset:1024
	ds_read_b128 v[160:163], v151 offset:2048
	ds_read_b128 v[164:167], v151 offset:3072
	ds_read_b128 v[168:171], v152
	ds_read_b128 v[172:175], v152 offset:1024
	ds_read_b128 v[176:179], v152 offset:2048
	ds_read_b128 v[180:183], v152 offset:3072
	s_add_u32 s28, s26, 0xfffc0080
	s_addc_u32 s29, s27, -1
	s_cmp_eq_u32 s50, 12
	s_cselect_b32 s31, s17, s29
	s_cselect_b32 s30, s23, s28
	s_cselect_b32 s29, s15, s49
	s_cselect_b32 s28, s47, s48
	v_lshl_add_u64 v[218:219], s[26:27], 0, v[136:137]
	s_add_i32 m0, s25, 0xc000
	ds_read_b128 v[184:187], v153
	ds_read_b128 v[190:193], v153 offset:1024
	ds_read_b128 v[194:197], v153 offset:2048
	ds_read_b128 v[198:201], v153 offset:3072
	ds_read_b128 v[202:205], v153 offset:4096
	ds_read_b128 v[206:209], v153 offset:5120
	ds_read_b128 v[210:213], v153 offset:6144
	ds_read_b128 v[214:217], v153 offset:7168
	global_load_lds_dwordx4 v[218:219], off
	v_lshl_add_u64 v[218:219], s[26:27], 0, v[138:139]
	s_add_i32 m0, s25, 0xe000
	s_nop 0
	global_load_lds_dwordx4 v[218:219], off
	s_waitcnt vmcnt(8)
	s_waitcnt lgkmcnt(0)
	s_barrier
	s_setprio 1
	v_mfma_f32_16x16x32_bf16 v[124:127], v[144:147], v[184:187], 0
	v_mfma_f32_16x16x32_bf16 v[120:123], v[160:163], v[184:187], 0
	v_mfma_f32_16x16x32_bf16 v[108:111], v[144:147], v[194:197], 0
	v_mfma_f32_16x16x32_bf16 v[104:107], v[160:163], v[194:197], 0
	v_mfma_f32_16x16x32_bf16 v[92:95], v[144:147], v[202:205], 0
	v_mfma_f32_16x16x32_bf16 v[88:91], v[160:163], v[202:205], 0
	v_mfma_f32_16x16x32_bf16 v[76:79], v[144:147], v[210:213], 0
	v_mfma_f32_16x16x32_bf16 v[72:75], v[160:163], v[210:213], 0
	v_mfma_f32_16x16x32_bf16 v[124:127], v[156:159], v[190:193], v[124:127]
	v_mfma_f32_16x16x32_bf16 v[120:123], v[164:167], v[190:193], v[120:123]
	v_mfma_f32_16x16x32_bf16 v[108:111], v[156:159], v[198:201], v[108:111]
	v_mfma_f32_16x16x32_bf16 v[104:107], v[164:167], v[198:201], v[104:107]
	v_mfma_f32_16x16x32_bf16 v[92:95], v[156:159], v[206:209], v[92:95]
	v_mfma_f32_16x16x32_bf16 v[88:91], v[164:167], v[206:209], v[88:91]
	v_mfma_f32_16x16x32_bf16 v[76:79], v[156:159], v[214:217], v[76:79]
	v_mfma_f32_16x16x32_bf16 v[72:75], v[164:167], v[214:217], v[72:75]
	v_mfma_f32_16x16x32_bf16 v[116:119], v[168:171], v[184:187], 0
	v_mfma_f32_16x16x32_bf16 v[112:115], v[176:179], v[184:187], 0
	v_mfma_f32_16x16x32_bf16 v[100:103], v[168:171], v[194:197], 0
	v_mfma_f32_16x16x32_bf16 v[96:99], v[176:179], v[194:197], 0
	v_mfma_f32_16x16x32_bf16 v[84:87], v[168:171], v[202:205], 0
	v_mfma_f32_16x16x32_bf16 v[80:83], v[176:179], v[202:205], 0
	v_mfma_f32_16x16x32_bf16 v[68:71], v[168:171], v[210:213], 0
	v_mfma_f32_16x16x32_bf16 v[64:67], v[176:179], v[210:213], 0
	v_mfma_f32_16x16x32_bf16 v[116:119], v[172:175], v[190:193], v[116:119]
	v_mfma_f32_16x16x32_bf16 v[112:115], v[180:183], v[190:193], v[112:115]
	v_mfma_f32_16x16x32_bf16 v[100:103], v[172:175], v[198:201], v[100:103]
	v_mfma_f32_16x16x32_bf16 v[96:99], v[180:183], v[198:201], v[96:99]
	v_mfma_f32_16x16x32_bf16 v[84:87], v[172:175], v[206:209], v[84:87]
	v_mfma_f32_16x16x32_bf16 v[80:83], v[180:183], v[206:209], v[80:83]
	v_mfma_f32_16x16x32_bf16 v[68:71], v[172:175], v[214:217], v[68:71]
	v_mfma_f32_16x16x32_bf16 v[64:67], v[180:183], v[214:217], v[64:67]
	s_setprio 0
	s_barrier
	s_add_i32 s51, s45, s35
	v_lshl_add_u64 v[218:219], s[28:29], 0, v[130:131]
	s_mov_b32 m0, s51
	ds_read_b128 v[184:187], v153 offset:16384
	ds_read_b128 v[190:193], v153 offset:17408
	ds_read_b128 v[194:197], v153 offset:18432
	ds_read_b128 v[198:201], v153 offset:19456
	ds_read_b128 v[202:205], v153 offset:20480
	ds_read_b128 v[206:209], v153 offset:21504
	ds_read_b128 v[210:213], v153 offset:22528
	ds_read_b128 v[214:217], v153 offset:23552
	global_load_lds_dwordx4 v[218:219], off
	s_add_i32 m0, s51, 0x2000
	s_add_u32 s52, s28, 0x40000
	v_lshl_add_u64 v[220:221], s[28:29], 0, v[134:135]
	s_addc_u32 s53, s29, 0
	s_add_i32 s51, s46, s35
	global_load_lds_dwordx4 v[220:221], off
	v_lshl_add_u64 v[222:223], s[52:53], 0, v[130:131]
	s_mov_b32 m0, s51
	v_lshl_add_u64 v[224:225], s[30:31], 0, v[132:133]
	global_load_lds_dwordx4 v[222:223], off
	v_lshl_add_u64 v[222:223], s[52:53], 0, v[134:135]
	s_add_i32 m0, s51, 0x2000
	s_nop 0
	global_load_lds_dwordx4 v[222:223], off
	v_lshl_add_u64 v[222:223], s[30:31], 0, v[128:129]
	s_mov_b32 m0, s25
	s_nop 0
	global_load_lds_dwordx4 v[222:223], off
	s_mov_b32 m0, s36
	s_nop 0
	global_load_lds_dwordx4 v[224:225], off
	s_waitcnt vmcnt(8)
	s_waitcnt lgkmcnt(0)
	s_barrier
; #define PG8_STAGE(bufoff, gbase, voff) do { _Pragma("unroll") for (int _i = 0; _i < 2; ++_i) \
;         __builtin_amdgcn_global_load_lds((const unsigned*)((const char*)(gbase) + (voff)[_i]), (PG8_LAS unsigned*)(lds + (bufoff) + ldsw + _i * 8192), 16, 0, 0); } while (0)
; #define PG8_LDA(dst, b, h) do { _Pragma("unroll") for (int m = 0; m < 4; ++m) _Pragma("unroll") for (int k = 0; k < 2; ++k) dst[m][k] = *(const PG8_LAS bf16x8*)(lds + PG8_SA(b, h) + aoff + m * 2048 + k * 1024); } while (0)
; #define PG8_LDB(dst, b, h) do { _Pragma("unroll") for (int n = 0; n < 2; ++n) _Pragma("unroll") for (int k = 0; k < 2; ++k) dst[n][k] = *(const PG8_LAS bf16x8*)(lds + PG8_SB(b, h) + boff + n * 2048 + k * 1024); } while (0)
; #define PG8_MMA(ai, bj, At, Bt) do { __builtin_amdgcn_s_setprio(1); _Pragma("unroll") for (int m = 0; m < 4; ++m) _Pragma("unroll") for (int n = 0; n < 2; ++n) _Pragma("unroll") for (int k = 0; k < 2; ++k) \
;         acc[ai][bj][m][n] = __builtin_amdgcn_mfma_f32_16x16x32_bf16(Bt[n][k], At[m][k], acc[ai][bj][m][n], 0, 0, 0); __builtin_amdgcn_s_setprio(0); } while (0)
; #define PG8_WAIT_V(n) asm volatile("s_waitcnt vmcnt(" #n ")" ::: "memory")
; #define PG8_WAIT_L(n) asm volatile("s_waitcnt lgkmcnt(" #n ")" ::: "memory")
; #define PG8_BAR __builtin_amdgcn_s_barrier()
; #define PG8_SCHED __builtin_amdgcn_sched_barrier(0)
; template <class Epi, class Sched, bool ALIGN_EPI = false, bool SP2 = false>
; __device__ __forceinline__ void gemm_phase(PG8_LAS unsigned char* lds, const Gemm g, const Sched& S, const Epi& E) {
;     ...
;             PG8_WAIT_V(8); PG8_WAIT_L(0); PG8_BAR; PG8_MMA(1, 0, At, B0); PG8_MMA(1, 1, At, B1); PG8_BAR; PG8_SCHED;
;             PG8_LDB(B0, 1, 0); PG8_LDB(B1, 1, 1); PG8_SCHED; PG8_LDA(At, 1, 0); PG8_STAGE(PG8_SA(0, 1), a2 + hstep, voffA);
;             PG8_WAIT_V(8); PG8_WAIT_L(0); PG8_BAR; PG8_MMA(0, 0, At, B0); PG8_MMA(0, 1, At, B1); PG8_BAR; PG8_SCHED;
	s_setprio 1
	v_mfma_f32_16x16x32_bf16 v[60:63], v[144:147], v[184:187], 0
	v_mfma_f32_16x16x32_bf16 v[56:59], v[160:163], v[184:187], 0
	v_mfma_f32_16x16x32_bf16 v[44:47], v[144:147], v[194:197], 0
	v_mfma_f32_16x16x32_bf16 v[40:43], v[160:163], v[194:197], 0
	v_mfma_f32_16x16x32_bf16 v[28:31], v[144:147], v[202:205], 0
	v_mfma_f32_16x16x32_bf16 v[24:27], v[160:163], v[202:205], 0
	v_mfma_f32_16x16x32_bf16 v[12:15], v[144:147], v[210:213], 0
	v_mfma_f32_16x16x32_bf16 v[8:11], v[160:163], v[210:213], 0
	v_mfma_f32_16x16x32_bf16 v[60:63], v[156:159], v[190:193], v[60:63]
	v_mfma_f32_16x16x32_bf16 v[56:59], v[164:167], v[190:193], v[56:59]
	v_mfma_f32_16x16x32_bf16 v[44:47], v[156:159], v[198:201], v[44:47]
	v_mfma_f32_16x16x32_bf16 v[40:43], v[164:167], v[198:201], v[40:43]
	v_mfma_f32_16x16x32_bf16 v[28:31], v[156:159], v[206:209], v[28:31]
	v_mfma_f32_16x16x32_bf16 v[24:27], v[164:167], v[206:209], v[24:27]
	v_mfma_f32_16x16x32_bf16 v[12:15], v[156:159], v[214:217], v[12:15]
	v_mfma_f32_16x16x32_bf16 v[8:11], v[164:167], v[214:217], v[8:11]
	v_mfma_f32_16x16x32_bf16 v[52:55], v[168:171], v[184:187], 0
	v_mfma_f32_16x16x32_bf16 v[48:51], v[176:179], v[184:187], 0
	v_mfma_f32_16x16x32_bf16 v[36:39], v[168:171], v[194:197], 0
	v_mfma_f32_16x16x32_bf16 v[32:35], v[176:179], v[194:197], 0
	v_mfma_f32_16x16x32_bf16 v[20:23], v[168:171], v[202:205], 0
	v_mfma_f32_16x16x32_bf16 v[16:19], v[176:179], v[202:205], 0
	v_mfma_f32_16x16x32_bf16 v[4:7], v[168:171], v[210:213], 0
	v_mfma_f32_16x16x32_bf16 v[0:3], v[176:179], v[210:213], 0
	v_mfma_f32_16x16x32_bf16 v[52:55], v[172:175], v[190:193], v[52:55]
	v_mfma_f32_16x16x32_bf16 v[48:51], v[180:183], v[190:193], v[48:51]
	v_mfma_f32_16x16x32_bf16 v[36:39], v[172:175], v[198:201], v[36:39]
	v_mfma_f32_16x16x32_bf16 v[32:35], v[180:183], v[198:201], v[32:35]
	v_mfma_f32_16x16x32_bf16 v[20:23], v[172:175], v[206:209], v[20:23]
	v_mfma_f32_16x16x32_bf16 v[16:19], v[180:183], v[206:209], v[16:19]
	v_mfma_f32_16x16x32_bf16 v[4:7], v[172:175], v[214:217], v[4:7]
	v_mfma_f32_16x16x32_bf16 v[0:3], v[180:183], v[214:217], v[0:3]
	s_setprio 0
	s_barrier
	s_add_i32 s51, 0, 0x18000
	v_add_u32_e32 v155, s51, v149
	s_add_i32 s52, 0, 0x1c000
	ds_read_b128 v[144:147], v155
	ds_read_b128 v[156:159], v155 offset:1024
	ds_read_b128 v[160:163], v155 offset:2048
	ds_read_b128 v[164:167], v155 offset:3072
	v_add_u32_e32 v155, s52, v149
	ds_read_b128 v[168:171], v155
	ds_read_b128 v[172:175], v155 offset:1024
	ds_read_b128 v[176:179], v155 offset:2048
	ds_read_b128 v[180:183], v155 offset:3072
	s_add_u32 s30, s30, 0x40000
	s_addc_u32 s31, s31, 0
	s_mov_b32 m0, s37
	v_lshl_add_u64 v[226:227], s[30:31], 0, v[128:129]
	ds_read_b128 v[184:187], v153 offset:32768
	ds_read_b128 v[190:193], v153 offset:33792
	ds_read_b128 v[194:197], v153 offset:34816
	ds_read_b128 v[198:201], v153 offset:35840
	ds_read_b128 v[202:205], v153 offset:36864
	ds_read_b128 v[206:209], v153 offset:37888
	ds_read_b128 v[210:213], v153 offset:38912
	ds_read_b128 v[214:217], v153 offset:39936
	global_load_lds_dwordx4 v[226:227], off
	v_lshl_add_u64 v[226:227], s[30:31], 0, v[132:133]
	s_mov_b32 m0, s38
	s_nop 0
	global_load_lds_dwordx4 v[226:227], off
	s_waitcnt vmcnt(8)
	s_waitcnt lgkmcnt(0)
	s_barrier
	s_setprio 1
	v_mfma_f32_16x16x32_bf16 v[124:127], v[144:147], v[184:187], v[124:127]
	v_mfma_f32_16x16x32_bf16 v[120:123], v[160:163], v[184:187], v[120:123]
	v_mfma_f32_16x16x32_bf16 v[108:111], v[144:147], v[194:197], v[108:111]
	v_mfma_f32_16x16x32_bf16 v[104:107], v[160:163], v[194:197], v[104:107]
	v_mfma_f32_16x16x32_bf16 v[92:95], v[144:147], v[202:205], v[92:95]
	v_mfma_f32_16x16x32_bf16 v[88:91], v[160:163], v[202:205], v[88:91]
	v_mfma_f32_16x16x32_bf16 v[76:79], v[144:147], v[210:213], v[76:79]
	v_mfma_f32_16x16x32_bf16 v[72:75], v[160:163], v[210:213], v[72:75]
	v_mfma_f32_16x16x32_bf16 v[124:127], v[156:159], v[190:193], v[124:127]
	v_mfma_f32_16x16x32_bf16 v[120:123], v[164:167], v[190:193], v[120:123]
	v_mfma_f32_16x16x32_bf16 v[108:111], v[156:159], v[198:201], v[108:111]
	v_mfma_f32_16x16x32_bf16 v[104:107], v[164:167], v[198:201], v[104:107]
	v_mfma_f32_16x16x32_bf16 v[92:95], v[156:159], v[206:209], v[92:95]
	v_mfma_f32_16x16x32_bf16 v[88:91], v[164:167], v[206:209], v[88:91]
	v_mfma_f32_16x16x32_bf16 v[76:79], v[156:159], v[214:217], v[76:79]
	v_mfma_f32_16x16x32_bf16 v[72:75], v[164:167], v[214:217], v[72:75]
	v_mfma_f32_16x16x32_bf16 v[116:119], v[168:171], v[184:187], v[116:119]
	v_mfma_f32_16x16x32_bf16 v[112:115], v[176:179], v[184:187], v[112:115]
	v_mfma_f32_16x16x32_bf16 v[100:103], v[168:171], v[194:197], v[100:103]
	v_mfma_f32_16x16x32_bf16 v[96:99], v[176:179], v[194:197], v[96:99]
	v_mfma_f32_16x16x32_bf16 v[84:87], v[168:171], v[202:205], v[84:87]
	v_mfma_f32_16x16x32_bf16 v[80:83], v[176:179], v[202:205], v[80:83]
	v_mfma_f32_16x16x32_bf16 v[68:71], v[168:171], v[210:213], v[68:71]
	v_mfma_f32_16x16x32_bf16 v[64:67], v[176:179], v[210:213], v[64:67]
	v_mfma_f32_16x16x32_bf16 v[116:119], v[172:175], v[190:193], v[116:119]
	v_mfma_f32_16x16x32_bf16 v[112:115], v[180:183], v[190:193], v[112:115]
	v_mfma_f32_16x16x32_bf16 v[100:103], v[172:175], v[198:201], v[100:103]
	v_mfma_f32_16x16x32_bf16 v[96:99], v[180:183], v[198:201], v[96:99]
	v_mfma_f32_16x16x32_bf16 v[84:87], v[172:175], v[206:209], v[84:87]
	v_mfma_f32_16x16x32_bf16 v[80:83], v[180:183], v[206:209], v[80:83]
	v_mfma_f32_16x16x32_bf16 v[68:71], v[172:175], v[214:217], v[68:71]
	v_mfma_f32_16x16x32_bf16 v[64:67], v[180:183], v[214:217], v[64:67]
	s_setprio 0
	s_barrier
; #define PG8_STAGE(bufoff, gbase, voff) do { _Pragma("unroll") for (int _i = 0; _i < 2; ++_i) \
;         __builtin_amdgcn_global_load_lds((const unsigned*)((const char*)(gbase) + (voff)[_i]), (PG8_LAS unsigned*)(lds + (bufoff) + ldsw + _i * 8192), 16, 0, 0); } while (0)
; #define PG8_LDA(dst, b, h) do { _Pragma("unroll") for (int m = 0; m < 4; ++m) _Pragma("unroll") for (int k = 0; k < 2; ++k) dst[m][k] = *(const PG8_LAS bf16x8*)(lds + PG8_SA(b, h) + aoff + m * 2048 + k * 1024); } while (0)
; #define PG8_MMA(ai, bj, At, Bt) do { __builtin_amdgcn_s_setprio(1); _Pragma("unroll") for (int m = 0; m < 4; ++m) _Pragma("unroll") for (int n = 0; n < 2; ++n) _Pragma("unroll") for (int k = 0; k < 2; ++k) \
;         acc[ai][bj][m][n] = __builtin_amdgcn_mfma_f32_16x16x32_bf16(Bt[n][k], At[m][k], acc[ai][bj][m][n], 0, 0, 0); __builtin_amdgcn_s_setprio(0); } while (0)
; #define PG8_WAIT_V(n) asm volatile("s_waitcnt vmcnt(" #n ")" ::: "memory")
; #define PG8_WAIT_L(n) asm volatile("s_waitcnt lgkmcnt(" #n ")" ::: "memory")
; #define PG8_BAR __builtin_amdgcn_s_barrier()
; #define PG8_SCHED __builtin_amdgcn_sched_barrier(0)
; template <class Epi, class Sched, bool ALIGN_EPI = false, bool SP2 = false>
; __device__ __forceinline__ void gemm_phase(PG8_LAS unsigned char* lds, const Gemm g, const Sched& S, const Epi& E) {
;     ...
;             PG8_LDA(At, 1, 1); PG8_STAGE(PG8_SB(1, 0), b3, voffB); PG8_STAGE(PG8_SB(1, 1), b3 + hstep, voffB); PG8_STAGE(PG8_SA(1, 0), a3, voffA);
;             PG8_WAIT_V(8); PG8_WAIT_L(0); PG8_BAR; PG8_MMA(1, 0, At, B0); PG8_MMA(1, 1, At, B1); PG8_BAR; PG8_SCHED;
	s_add_i32 s30, s51, s35
	v_lshl_add_u64 v[218:219], v[218:219], 0, s[2:3]
	s_mov_b32 m0, s30
	ds_read_b128 v[184:187], v153 offset:49152
	ds_read_b128 v[190:193], v153 offset:50176
	ds_read_b128 v[194:197], v153 offset:51200
	ds_read_b128 v[198:201], v153 offset:52224
	ds_read_b128 v[202:205], v153 offset:53248
	ds_read_b128 v[206:209], v153 offset:54272
	ds_read_b128 v[210:213], v153 offset:55296
	ds_read_b128 v[214:217], v153 offset:56320
	global_load_lds_dwordx4 v[218:219], off
	s_add_i32 m0, s30, 0x2000
	s_add_u32 s28, s28, 0x40080
	v_lshl_add_u64 v[218:219], v[220:221], 0, s[2:3]
	s_addc_u32 s29, s29, 0
	s_add_i32 s30, s52, s35
	global_load_lds_dwordx4 v[218:219], off
	v_lshl_add_u64 v[218:219], s[28:29], 0, v[130:131]
	s_mov_b32 m0, s30
	s_nop 0
	global_load_lds_dwordx4 v[218:219], off
	v_lshl_add_u64 v[218:219], s[28:29], 0, v[134:135]
	s_add_i32 m0, s30, 0x2000
	s_nop 0
	global_load_lds_dwordx4 v[218:219], off
	v_lshl_add_u64 v[218:219], v[222:223], 0, s[2:3]
	s_mov_b32 m0, s40
	s_nop 0
	global_load_lds_dwordx4 v[218:219], off
	v_lshl_add_u64 v[218:219], v[224:225], 0, s[2:3]
	s_mov_b32 m0, s41
	s_nop 0
	global_load_lds_dwordx4 v[218:219], off
	s_waitcnt vmcnt(8)
	s_waitcnt lgkmcnt(0)
	s_barrier
	s_setprio 1
	v_mfma_f32_16x16x32_bf16 v[60:63], v[144:147], v[184:187], v[60:63]
	v_mfma_f32_16x16x32_bf16 v[56:59], v[160:163], v[184:187], v[56:59]
	v_mfma_f32_16x16x32_bf16 v[44:47], v[144:147], v[194:197], v[44:47]
	v_mfma_f32_16x16x32_bf16 v[40:43], v[160:163], v[194:197], v[40:43]
	v_mfma_f32_16x16x32_bf16 v[28:31], v[144:147], v[202:205], v[28:31]
	v_mfma_f32_16x16x32_bf16 v[24:27], v[160:163], v[202:205], v[24:27]
	v_mfma_f32_16x16x32_bf16 v[12:15], v[144:147], v[210:213], v[12:15]
	v_mfma_f32_16x16x32_bf16 v[8:11], v[160:163], v[210:213], v[8:11]
	v_mfma_f32_16x16x32_bf16 v[60:63], v[156:159], v[190:193], v[60:63]
	v_mfma_f32_16x16x32_bf16 v[56:59], v[164:167], v[190:193], v[56:59]
	v_mfma_f32_16x16x32_bf16 v[44:47], v[156:159], v[198:201], v[44:47]
	v_mfma_f32_16x16x32_bf16 v[40:43], v[164:167], v[198:201], v[40:43]
	v_mfma_f32_16x16x32_bf16 v[28:31], v[156:159], v[206:209], v[28:31]
	v_mfma_f32_16x16x32_bf16 v[24:27], v[164:167], v[206:209], v[24:27]
	v_mfma_f32_16x16x32_bf16 v[12:15], v[156:159], v[214:217], v[12:15]
	v_mfma_f32_16x16x32_bf16 v[8:11], v[164:167], v[214:217], v[8:11]
	v_mfma_f32_16x16x32_bf16 v[52:55], v[168:171], v[184:187], v[52:55]
	v_mfma_f32_16x16x32_bf16 v[48:51], v[176:179], v[184:187], v[48:51]
	v_mfma_f32_16x16x32_bf16 v[36:39], v[168:171], v[194:197], v[36:39]
	v_mfma_f32_16x16x32_bf16 v[32:35], v[176:179], v[194:197], v[32:35]
	v_mfma_f32_16x16x32_bf16 v[20:23], v[168:171], v[202:205], v[20:23]
	v_mfma_f32_16x16x32_bf16 v[16:19], v[176:179], v[202:205], v[16:19]
	v_mfma_f32_16x16x32_bf16 v[4:7], v[168:171], v[210:213], v[4:7]
	v_mfma_f32_16x16x32_bf16 v[0:3], v[176:179], v[210:213], v[0:3]
	v_mfma_f32_16x16x32_bf16 v[52:55], v[172:175], v[190:193], v[52:55]
	v_mfma_f32_16x16x32_bf16 v[48:51], v[180:183], v[190:193], v[48:51]
	v_mfma_f32_16x16x32_bf16 v[36:39], v[172:175], v[198:201], v[36:39]
	v_mfma_f32_16x16x32_bf16 v[32:35], v[180:183], v[198:201], v[32:35]
	v_mfma_f32_16x16x32_bf16 v[20:23], v[172:175], v[206:209], v[20:23]
	v_mfma_f32_16x16x32_bf16 v[16:19], v[180:183], v[206:209], v[16:19]
	v_mfma_f32_16x16x32_bf16 v[4:7], v[172:175], v[214:217], v[4:7]
	v_mfma_f32_16x16x32_bf16 v[0:3], v[180:183], v[214:217], v[0:3]
	s_setprio 0
	s_barrier
	s_add_i32 s50, s50, 2
	s_add_u32 s26, s26, 0x100
	s_addc_u32 s27, s27, 0
	s_add_u32 s48, s48, 0x100
	s_addc_u32 s49, s49, 0
	.p2alignl 6, 3212836864

; #define PG8_STAGE(bufoff, gbase, voff) do { _Pragma("unroll") for (int _i = 0; _i < 2; ++_i) \
;         __builtin_amdgcn_global_load_lds((const unsigned*)((const char*)(gbase) + (voff)[_i]), (PG8_LAS unsigned*)(lds + (bufoff) + ldsw + _i * 8192), 16, 0, 0); } while (0)
; #define PG8_LDA(dst, b, h) do { _Pragma("unroll") for (int m = 0; m < 4; ++m) _Pragma("unroll") for (int k = 0; k < 2; ++k) dst[m][k] = *(const PG8_LAS bf16x8*)(lds + PG8_SA(b, h) + aoff + m * 2048 + k * 1024); } while (0)
; #define PG8_LDB(dst, b, h) do { _Pragma("unroll") for (int n = 0; n < 2; ++n) _Pragma("unroll") for (int k = 0; k < 2; ++k) dst[n][k] = *(const PG8_LAS bf16x8*)(lds + PG8_SB(b, h) + boff + n * 2048 + k * 1024); } while (0)
; #define PG8_WAIT_V(n) asm volatile("s_waitcnt vmcnt(" #n ")" ::: "memory")
; #define PG8_WAIT_L(n) asm volatile("s_waitcnt lgkmcnt(" #n ")" ::: "memory")
; #define PG8_BAR __builtin_amdgcn_s_barrier()
; #define PG8_SCHED __builtin_amdgcn_sched_barrier(0)
; template <class Epi, class Sched, bool ALIGN_EPI = false, bool SP2 = false>
; __device__ __forceinline__ void gemm_phase(PG8_LAS unsigned char* lds, const Gemm g, const Sched& S, const Epi& E) {
;     ...
;         const bool has_next = S.next(ui + 1, nxt);
;         const char* nA = has_next ? (const char*)g.A + (size_t)nxt.pm * tstep : cA; const char* nB = has_next ? (const char*)g.Bt + (size_t)nxt.pn * tstep : cB;
;         for (int t = 0; t < nt; t += 2) {
;             const bool last = (t == nt - 2);
;             const char* a1 = cA + (size_t)(t + 1) * kstep;
;             const char* a2 = last ? nA : cA + (size_t)(t + 2) * kstep; const char* b2 = last ? nB : cB + (size_t)(t + 2) * kstep;
;             const char* a3 = a2 + kstep; const char* b3 = b2 + kstep;
;             if (last && has_next) S.a_ready(nxt);
;             if constexpr (SP2) {
;             PG8_LDB(B0, 0, 0); PG8_LDB(B1, 0, 1); PG8_SCHED; PG8_LDA(At, 0, 0); PG8_STAGE(PG8_SA(1, 1), a1 + hstep, voffA);
;             PG8_WAIT_V(8); PG8_WAIT_L(0); PG8_BAR; PG8_MMA(0, 0, At, B0); PG8_MMA(0, 1, At, B1); PG8_BAR; PG8_SCHED;
;             PG8_LDA(At, 0, 1); PG8_STAGE(PG8_SB(0, 0), b2, voffB); PG8_STAGE(PG8_SB(0, 1), b2 + hstep, voffB); PG8_STAGE(PG8_SA(0, 0), a2, voffA);
;             PG8_WAIT_V(8); PG8_WAIT_L(0); PG8_BAR; PG8_MMA(1, 0, At, B0); PG8_MMA(1, 1, At, B1); PG8_BAR; PG8_SCHED;
.LBB0_781:
	s_ashr_i32 s17, s16, 31
	s_lshl_b64 s[18:19], s[16:17], 19
	s_add_u32 s18, s8, s18
	s_addc_u32 s19, s9, s19
	s_and_b64 s[20:21], s[4:5], exec
	s_cselect_b32 s17, s19, s23
	s_cselect_b32 s47, s18, s22
	s_ashr_i32 s15, s14, 31
	s_lshl_b64 s[20:21], s[14:15], 19
	s_add_u32 s20, s28, s20
	s_addc_u32 s21, s29, s21
	s_and_b64 s[26:27], s[4:5], exec
	s_cselect_b32 s15, s21, s25
	s_cselect_b32 s48, s20, s24
	s_add_u32 s22, s22, 0x40080
	s_addc_u32 s23, s23, 0
	s_add_u32 s49, s24, 0x100
	s_addc_u32 s50, s25, 0
	s_mov_b32 s51, -2
	ds_read_b128 v[144:147], v151
	ds_read_b128 v[156:159], v151 offset:1024
	ds_read_b128 v[160:163], v151 offset:2048
	ds_read_b128 v[164:167], v151 offset:3072
	ds_read_b128 v[168:171], v152
	ds_read_b128 v[172:175], v152 offset:1024
	ds_read_b128 v[176:179], v152 offset:2048
	ds_read_b128 v[180:183], v152 offset:3072
	s_add_u32 s24, s22, 0xfffc0080
	s_addc_u32 s25, s23, -1
	s_cmp_eq_u32 s51, 12
	s_cselect_b32 s27, s17, s25
	s_cselect_b32 s26, s47, s24
	s_cselect_b32 s25, s15, s50
	s_cselect_b32 s24, s48, s49
	v_lshl_add_u64 v[218:219], s[22:23], 0, v[136:137]
	s_add_i32 m0, s34, 0xc000
	ds_read_b128 v[184:187], v153
	ds_read_b128 v[190:193], v153 offset:1024
	ds_read_b128 v[194:197], v153 offset:2048
	ds_read_b128 v[198:201], v153 offset:3072
	ds_read_b128 v[202:205], v153 offset:4096
	ds_read_b128 v[206:209], v153 offset:5120
	ds_read_b128 v[210:213], v153 offset:6144
	ds_read_b128 v[214:217], v153 offset:7168
	global_load_lds_dwordx4 v[218:219], off
	v_lshl_add_u64 v[218:219], s[22:23], 0, v[138:139]
	s_add_i32 m0, s34, 0xe000
	s_nop 0
	global_load_lds_dwordx4 v[218:219], off
	s_waitcnt vmcnt(16)
	s_waitcnt lgkmcnt(0)
	s_barrier
	s_setprio 1
	v_mfma_f32_16x16x32_bf16 v[116:119], v[144:147], v[184:187], 0
	v_mfma_f32_16x16x32_bf16 v[112:115], v[160:163], v[184:187], 0
	v_mfma_f32_16x16x32_bf16 v[100:103], v[144:147], v[194:197], 0
	v_mfma_f32_16x16x32_bf16 v[96:99], v[160:163], v[194:197], 0
	v_mfma_f32_16x16x32_bf16 v[84:87], v[144:147], v[202:205], 0
	v_mfma_f32_16x16x32_bf16 v[80:83], v[160:163], v[202:205], 0
	v_mfma_f32_16x16x32_bf16 v[72:75], v[144:147], v[210:213], 0
	v_mfma_f32_16x16x32_bf16 v[64:67], v[160:163], v[210:213], 0
	v_mfma_f32_16x16x32_bf16 v[116:119], v[156:159], v[190:193], v[116:119]
	v_mfma_f32_16x16x32_bf16 v[112:115], v[164:167], v[190:193], v[112:115]
	v_mfma_f32_16x16x32_bf16 v[100:103], v[156:159], v[198:201], v[100:103]
	v_mfma_f32_16x16x32_bf16 v[96:99], v[164:167], v[198:201], v[96:99]
	v_mfma_f32_16x16x32_bf16 v[84:87], v[156:159], v[206:209], v[84:87]
	v_mfma_f32_16x16x32_bf16 v[80:83], v[164:167], v[206:209], v[80:83]
	v_mfma_f32_16x16x32_bf16 v[72:75], v[156:159], v[214:217], v[72:75]
	v_mfma_f32_16x16x32_bf16 v[64:67], v[164:167], v[214:217], v[64:67]
	v_mfma_f32_16x16x32_bf16 v[124:127], v[168:171], v[184:187], 0
	v_mfma_f32_16x16x32_bf16 v[120:123], v[176:179], v[184:187], 0
	v_mfma_f32_16x16x32_bf16 v[108:111], v[168:171], v[194:197], 0
	v_mfma_f32_16x16x32_bf16 v[104:107], v[176:179], v[194:197], 0
	v_mfma_f32_16x16x32_bf16 v[92:95], v[168:171], v[202:205], 0
	v_mfma_f32_16x16x32_bf16 v[88:91], v[176:179], v[202:205], 0
	v_mfma_f32_16x16x32_bf16 v[76:79], v[168:171], v[210:213], 0
	v_mfma_f32_16x16x32_bf16 v[68:71], v[176:179], v[210:213], 0
	v_mfma_f32_16x16x32_bf16 v[124:127], v[172:175], v[190:193], v[124:127]
	v_mfma_f32_16x16x32_bf16 v[120:123], v[180:183], v[190:193], v[120:123]
	v_mfma_f32_16x16x32_bf16 v[108:111], v[172:175], v[198:201], v[108:111]
	v_mfma_f32_16x16x32_bf16 v[104:107], v[180:183], v[198:201], v[104:107]
	v_mfma_f32_16x16x32_bf16 v[92:95], v[172:175], v[206:209], v[92:95]
	v_mfma_f32_16x16x32_bf16 v[88:91], v[180:183], v[206:209], v[88:91]
	v_mfma_f32_16x16x32_bf16 v[76:79], v[172:175], v[214:217], v[76:79]
	v_mfma_f32_16x16x32_bf16 v[68:71], v[180:183], v[214:217], v[68:71]
	s_setprio 0
	s_barrier
	s_add_i32 s52, s43, s30
	v_lshl_add_u64 v[218:219], s[24:25], 0, v[132:133]
	s_mov_b32 m0, s52
	ds_read_b128 v[184:187], v153 offset:16384
	ds_read_b128 v[190:193], v153 offset:17408
	ds_read_b128 v[194:197], v153 offset:18432
	ds_read_b128 v[198:201], v153 offset:19456
	ds_read_b128 v[202:205], v153 offset:20480
	ds_read_b128 v[206:209], v153 offset:21504
	ds_read_b128 v[210:213], v153 offset:22528
	ds_read_b128 v[214:217], v153 offset:23552
	global_load_lds_dwordx4 v[218:219], off
	s_add_i32 m0, s52, 0x2000
	s_add_u32 s52, s24, 0x40000
	v_lshl_add_u64 v[220:221], s[24:25], 0, v[128:129]
	s_addc_u32 s53, s25, 0
	s_add_i32 s54, s44, s30
	global_load_lds_dwordx4 v[220:221], off
	v_lshl_add_u64 v[222:223], s[52:53], 0, v[132:133]
	s_mov_b32 m0, s54
	v_lshl_add_u64 v[224:225], s[26:27], 0, v[130:131]
	global_load_lds_dwordx4 v[222:223], off
	v_lshl_add_u64 v[222:223], s[52:53], 0, v[128:129]
	s_add_i32 m0, s54, 0x2000
	s_nop 0
	global_load_lds_dwordx4 v[222:223], off
	v_lshl_add_u64 v[222:223], s[26:27], 0, v[134:135]
	s_mov_b32 m0, s34
	s_nop 0
	global_load_lds_dwordx4 v[222:223], off
	s_mov_b32 m0, s35
	s_nop 0
	global_load_lds_dwordx4 v[224:225], off
	s_waitcnt vmcnt(16)
	s_waitcnt lgkmcnt(0)
	s_barrier
; #define PG8_STAGE(bufoff, gbase, voff) do { _Pragma("unroll") for (int _i = 0; _i < 2; ++_i) \
;         __builtin_amdgcn_global_load_lds((const unsigned*)((const char*)(gbase) + (voff)[_i]), (PG8_LAS unsigned*)(lds + (bufoff) + ldsw + _i * 8192), 16, 0, 0); } while (0)
; #define PG8_LDA(dst, b, h) do { _Pragma("unroll") for (int m = 0; m < 4; ++m) _Pragma("unroll") for (int k = 0; k < 2; ++k) dst[m][k] = *(const PG8_LAS bf16x8*)(lds + PG8_SA(b, h) + aoff + m * 2048 + k * 1024); } while (0)
; #define PG8_LDB(dst, b, h) do { _Pragma("unroll") for (int n = 0; n < 2; ++n) _Pragma("unroll") for (int k = 0; k < 2; ++k) dst[n][k] = *(const PG8_LAS bf16x8*)(lds + PG8_SB(b, h) + boff + n * 2048 + k * 1024); } while (0)
; #define PG8_MMA(ai, bj, At, Bt) do { __builtin_amdgcn_s_setprio(1); _Pragma("unroll") for (int m = 0; m < 4; ++m) _Pragma("unroll") for (int n = 0; n < 2; ++n) _Pragma("unroll") for (int k = 0; k < 2; ++k) \
;         acc[ai][bj][m][n] = __builtin_amdgcn_mfma_f32_16x16x32_bf16(Bt[n][k], At[m][k], acc[ai][bj][m][n], 0, 0, 0); __builtin_amdgcn_s_setprio(0); } while (0)
; #define PG8_WAIT_V(n) asm volatile("s_waitcnt vmcnt(" #n ")" ::: "memory")
; #define PG8_WAIT_L(n) asm volatile("s_waitcnt lgkmcnt(" #n ")" ::: "memory")
; #define PG8_BAR __builtin_amdgcn_s_barrier()
; #define PG8_SCHED __builtin_amdgcn_sched_barrier(0)
; template <class Epi, class Sched, bool ALIGN_EPI = false, bool SP2 = false>
; __device__ __forceinline__ void gemm_phase(PG8_LAS unsigned char* lds, const Gemm g, const Sched& S, const Epi& E) {
;     ...
;             PG8_WAIT_V(8); PG8_WAIT_L(0); PG8_BAR; PG8_MMA(1, 0, At, B0); PG8_MMA(1, 1, At, B1); PG8_BAR; PG8_SCHED;
;             PG8_LDB(B0, 1, 0); PG8_LDB(B1, 1, 1); PG8_SCHED; PG8_LDA(At, 1, 0); PG8_STAGE(PG8_SA(0, 1), a2 + hstep, voffA);
;             PG8_WAIT_V(8); PG8_WAIT_L(0); PG8_BAR; PG8_MMA(0, 0, At, B0); PG8_MMA(0, 1, At, B1); PG8_BAR; PG8_SCHED;
	s_setprio 1
	v_mfma_f32_16x16x32_bf16 v[56:59], v[144:147], v[184:187], 0
	v_mfma_f32_16x16x32_bf16 v[48:51], v[160:163], v[184:187], 0
	v_mfma_f32_16x16x32_bf16 v[40:43], v[144:147], v[194:197], 0
	v_mfma_f32_16x16x32_bf16 v[32:35], v[160:163], v[194:197], 0
	v_mfma_f32_16x16x32_bf16 v[24:27], v[144:147], v[202:205], 0
	v_mfma_f32_16x16x32_bf16 v[16:19], v[160:163], v[202:205], 0
	v_mfma_f32_16x16x32_bf16 v[8:11], v[144:147], v[210:213], 0
	v_mfma_f32_16x16x32_bf16 v[0:3], v[160:163], v[210:213], 0
	v_mfma_f32_16x16x32_bf16 v[56:59], v[156:159], v[190:193], v[56:59]
	v_mfma_f32_16x16x32_bf16 v[48:51], v[164:167], v[190:193], v[48:51]
	v_mfma_f32_16x16x32_bf16 v[40:43], v[156:159], v[198:201], v[40:43]
	v_mfma_f32_16x16x32_bf16 v[32:35], v[164:167], v[198:201], v[32:35]
	v_mfma_f32_16x16x32_bf16 v[24:27], v[156:159], v[206:209], v[24:27]
	v_mfma_f32_16x16x32_bf16 v[16:19], v[164:167], v[206:209], v[16:19]
	v_mfma_f32_16x16x32_bf16 v[8:11], v[156:159], v[214:217], v[8:11]
	v_mfma_f32_16x16x32_bf16 v[0:3], v[164:167], v[214:217], v[0:3]
	v_mfma_f32_16x16x32_bf16 v[60:63], v[168:171], v[184:187], 0
	v_mfma_f32_16x16x32_bf16 v[52:55], v[176:179], v[184:187], 0
	v_mfma_f32_16x16x32_bf16 v[44:47], v[168:171], v[194:197], 0
	v_mfma_f32_16x16x32_bf16 v[36:39], v[176:179], v[194:197], 0
	v_mfma_f32_16x16x32_bf16 v[28:31], v[168:171], v[202:205], 0
	v_mfma_f32_16x16x32_bf16 v[20:23], v[176:179], v[202:205], 0
	v_mfma_f32_16x16x32_bf16 v[12:15], v[168:171], v[210:213], 0
	v_mfma_f32_16x16x32_bf16 v[4:7], v[176:179], v[210:213], 0
	v_mfma_f32_16x16x32_bf16 v[60:63], v[172:175], v[190:193], v[60:63]
	v_mfma_f32_16x16x32_bf16 v[52:55], v[180:183], v[190:193], v[52:55]
	v_mfma_f32_16x16x32_bf16 v[44:47], v[172:175], v[198:201], v[44:47]
	v_mfma_f32_16x16x32_bf16 v[36:39], v[180:183], v[198:201], v[36:39]
	v_mfma_f32_16x16x32_bf16 v[28:31], v[172:175], v[206:209], v[28:31]
	v_mfma_f32_16x16x32_bf16 v[20:23], v[180:183], v[206:209], v[20:23]
	v_mfma_f32_16x16x32_bf16 v[12:15], v[172:175], v[214:217], v[12:15]
	v_mfma_f32_16x16x32_bf16 v[4:7], v[180:183], v[214:217], v[4:7]
	s_setprio 0
	s_barrier
	s_add_i32 s52, 0, 0x18000
	v_add_u32_e32 v155, s52, v149
	s_add_i32 s53, 0, 0x1c000
	ds_read_b128 v[144:147], v155
	ds_read_b128 v[156:159], v155 offset:1024
	ds_read_b128 v[160:163], v155 offset:2048
	ds_read_b128 v[164:167], v155 offset:3072
	v_add_u32_e32 v155, s53, v149
	ds_read_b128 v[168:171], v155
	ds_read_b128 v[172:175], v155 offset:1024
	ds_read_b128 v[176:179], v155 offset:2048
	ds_read_b128 v[180:183], v155 offset:3072
	s_add_u32 s26, s26, 0x40000
	s_addc_u32 s27, s27, 0
	s_mov_b32 m0, s36
	v_lshl_add_u64 v[226:227], s[26:27], 0, v[134:135]
	ds_read_b128 v[184:187], v153 offset:32768
	ds_read_b128 v[190:193], v153 offset:33792
	ds_read_b128 v[194:197], v153 offset:34816
	ds_read_b128 v[198:201], v153 offset:35840
	ds_read_b128 v[202:205], v153 offset:36864
	ds_read_b128 v[206:209], v153 offset:37888
	ds_read_b128 v[210:213], v153 offset:38912
	ds_read_b128 v[214:217], v153 offset:39936
	global_load_lds_dwordx4 v[226:227], off
	v_lshl_add_u64 v[226:227], s[26:27], 0, v[130:131]
	s_mov_b32 m0, s37
	s_nop 0
	global_load_lds_dwordx4 v[226:227], off
	s_waitcnt vmcnt(8)
	s_waitcnt lgkmcnt(0)
	s_barrier
	s_setprio 1
	v_mfma_f32_16x16x32_bf16 v[116:119], v[144:147], v[184:187], v[116:119]
	v_mfma_f32_16x16x32_bf16 v[112:115], v[160:163], v[184:187], v[112:115]
	v_mfma_f32_16x16x32_bf16 v[100:103], v[144:147], v[194:197], v[100:103]
	v_mfma_f32_16x16x32_bf16 v[96:99], v[160:163], v[194:197], v[96:99]
	v_mfma_f32_16x16x32_bf16 v[84:87], v[144:147], v[202:205], v[84:87]
	v_mfma_f32_16x16x32_bf16 v[80:83], v[160:163], v[202:205], v[80:83]
	v_mfma_f32_16x16x32_bf16 v[72:75], v[144:147], v[210:213], v[72:75]
	v_mfma_f32_16x16x32_bf16 v[64:67], v[160:163], v[210:213], v[64:67]
	v_mfma_f32_16x16x32_bf16 v[116:119], v[156:159], v[190:193], v[116:119]
	v_mfma_f32_16x16x32_bf16 v[112:115], v[164:167], v[190:193], v[112:115]
	v_mfma_f32_16x16x32_bf16 v[100:103], v[156:159], v[198:201], v[100:103]
	v_mfma_f32_16x16x32_bf16 v[96:99], v[164:167], v[198:201], v[96:99]
	v_mfma_f32_16x16x32_bf16 v[84:87], v[156:159], v[206:209], v[84:87]
	v_mfma_f32_16x16x32_bf16 v[80:83], v[164:167], v[206:209], v[80:83]
	v_mfma_f32_16x16x32_bf16 v[72:75], v[156:159], v[214:217], v[72:75]
	v_mfma_f32_16x16x32_bf16 v[64:67], v[164:167], v[214:217], v[64:67]
	v_mfma_f32_16x16x32_bf16 v[124:127], v[168:171], v[184:187], v[124:127]
	v_mfma_f32_16x16x32_bf16 v[120:123], v[176:179], v[184:187], v[120:123]
	v_mfma_f32_16x16x32_bf16 v[108:111], v[168:171], v[194:197], v[108:111]
	v_mfma_f32_16x16x32_bf16 v[104:107], v[176:179], v[194:197], v[104:107]
	v_mfma_f32_16x16x32_bf16 v[92:95], v[168:171], v[202:205], v[92:95]
	v_mfma_f32_16x16x32_bf16 v[88:91], v[176:179], v[202:205], v[88:91]
	v_mfma_f32_16x16x32_bf16 v[76:79], v[168:171], v[210:213], v[76:79]
	v_mfma_f32_16x16x32_bf16 v[68:71], v[176:179], v[210:213], v[68:71]
	v_mfma_f32_16x16x32_bf16 v[124:127], v[172:175], v[190:193], v[124:127]
	v_mfma_f32_16x16x32_bf16 v[120:123], v[180:183], v[190:193], v[120:123]
	v_mfma_f32_16x16x32_bf16 v[108:111], v[172:175], v[198:201], v[108:111]
	v_mfma_f32_16x16x32_bf16 v[104:107], v[180:183], v[198:201], v[104:107]
	v_mfma_f32_16x16x32_bf16 v[92:95], v[172:175], v[206:209], v[92:95]
	v_mfma_f32_16x16x32_bf16 v[88:91], v[180:183], v[206:209], v[88:91]
	v_mfma_f32_16x16x32_bf16 v[76:79], v[172:175], v[214:217], v[76:79]
	v_mfma_f32_16x16x32_bf16 v[68:71], v[180:183], v[214:217], v[68:71]
	s_setprio 0
	s_barrier
; #define PG8_STAGE(bufoff, gbase, voff) do { _Pragma("unroll") for (int _i = 0; _i < 2; ++_i) \
;         __builtin_amdgcn_global_load_lds((const unsigned*)((const char*)(gbase) + (voff)[_i]), (PG8_LAS unsigned*)(lds + (bufoff) + ldsw + _i * 8192), 16, 0, 0); } while (0)
; #define PG8_LDA(dst, b, h) do { _Pragma("unroll") for (int m = 0; m < 4; ++m) _Pragma("unroll") for (int k = 0; k < 2; ++k) dst[m][k] = *(const PG8_LAS bf16x8*)(lds + PG8_SA(b, h) + aoff + m * 2048 + k * 1024); } while (0)
; #define PG8_MMA(ai, bj, At, Bt) do { __builtin_amdgcn_s_setprio(1); _Pragma("unroll") for (int m = 0; m < 4; ++m) _Pragma("unroll") for (int n = 0; n < 2; ++n) _Pragma("unroll") for (int k = 0; k < 2; ++k) \
;         acc[ai][bj][m][n] = __builtin_amdgcn_mfma_f32_16x16x32_bf16(Bt[n][k], At[m][k], acc[ai][bj][m][n], 0, 0, 0); __builtin_amdgcn_s_setprio(0); } while (0)
; #define PG8_WAIT_V(n) asm volatile("s_waitcnt vmcnt(" #n ")" ::: "memory")
; #define PG8_WAIT_L(n) asm volatile("s_waitcnt lgkmcnt(" #n ")" ::: "memory")
; #define PG8_BAR __builtin_amdgcn_s_barrier()
; #define PG8_SCHED __builtin_amdgcn_sched_barrier(0)
; template <class Epi, class Sched, bool ALIGN_EPI = false, bool SP2 = false>
; __device__ __forceinline__ void gemm_phase(PG8_LAS unsigned char* lds, const Gemm g, const Sched& S, const Epi& E) {
;     ...
;             PG8_LDA(At, 1, 1); PG8_STAGE(PG8_SB(1, 0), b3, voffB); PG8_STAGE(PG8_SB(1, 1), b3 + hstep, voffB); PG8_STAGE(PG8_SA(1, 0), a3, voffA);
;             PG8_WAIT_V(8); PG8_WAIT_L(0); PG8_BAR; PG8_MMA(1, 0, At, B0); PG8_MMA(1, 1, At, B1); PG8_BAR; PG8_SCHED;
	s_add_i32 s26, s52, s30
	v_lshl_add_u64 v[218:219], v[218:219], 0, s[6:7]
	s_mov_b32 m0, s26
	ds_read_b128 v[184:187], v153 offset:49152
	ds_read_b128 v[190:193], v153 offset:50176
	ds_read_b128 v[194:197], v153 offset:51200
	ds_read_b128 v[198:201], v153 offset:52224
	ds_read_b128 v[202:205], v153 offset:53248
	ds_read_b128 v[206:209], v153 offset:54272
	ds_read_b128 v[210:213], v153 offset:55296
	ds_read_b128 v[214:217], v153 offset:56320
	global_load_lds_dwordx4 v[218:219], off
	s_add_i32 m0, s26, 0x2000
	s_add_u32 s24, s24, 0x40080
	v_lshl_add_u64 v[218:219], v[220:221], 0, s[6:7]
	s_addc_u32 s25, s25, 0
	s_add_i32 s26, s53, s30
	global_load_lds_dwordx4 v[218:219], off
	v_lshl_add_u64 v[218:219], s[24:25], 0, v[132:133]
	s_mov_b32 m0, s26
	s_nop 0
	global_load_lds_dwordx4 v[218:219], off
	v_lshl_add_u64 v[218:219], s[24:25], 0, v[128:129]
	s_add_i32 m0, s26, 0x2000
	s_nop 0
	global_load_lds_dwordx4 v[218:219], off
	v_lshl_add_u64 v[218:219], v[222:223], 0, s[6:7]
	s_mov_b32 m0, s39
	s_nop 0
	global_load_lds_dwordx4 v[218:219], off
	v_lshl_add_u64 v[218:219], v[224:225], 0, s[6:7]
	s_mov_b32 m0, s40
	s_nop 0
	global_load_lds_dwordx4 v[218:219], off
	s_waitcnt vmcnt(8)
	s_waitcnt lgkmcnt(0)
	s_barrier
	s_setprio 1
	v_mfma_f32_16x16x32_bf16 v[56:59], v[144:147], v[184:187], v[56:59]
	v_mfma_f32_16x16x32_bf16 v[48:51], v[160:163], v[184:187], v[48:51]
	v_mfma_f32_16x16x32_bf16 v[40:43], v[144:147], v[194:197], v[40:43]
	v_mfma_f32_16x16x32_bf16 v[32:35], v[160:163], v[194:197], v[32:35]
	v_mfma_f32_16x16x32_bf16 v[24:27], v[144:147], v[202:205], v[24:27]
	v_mfma_f32_16x16x32_bf16 v[16:19], v[160:163], v[202:205], v[16:19]
	v_mfma_f32_16x16x32_bf16 v[8:11], v[144:147], v[210:213], v[8:11]
	v_mfma_f32_16x16x32_bf16 v[0:3], v[160:163], v[210:213], v[0:3]
	v_mfma_f32_16x16x32_bf16 v[56:59], v[156:159], v[190:193], v[56:59]
	v_mfma_f32_16x16x32_bf16 v[48:51], v[164:167], v[190:193], v[48:51]
	v_mfma_f32_16x16x32_bf16 v[40:43], v[156:159], v[198:201], v[40:43]
	v_mfma_f32_16x16x32_bf16 v[32:35], v[164:167], v[198:201], v[32:35]
	v_mfma_f32_16x16x32_bf16 v[24:27], v[156:159], v[206:209], v[24:27]
	v_mfma_f32_16x16x32_bf16 v[16:19], v[164:167], v[206:209], v[16:19]
	v_mfma_f32_16x16x32_bf16 v[8:11], v[156:159], v[214:217], v[8:11]
	v_mfma_f32_16x16x32_bf16 v[0:3], v[164:167], v[214:217], v[0:3]
	v_mfma_f32_16x16x32_bf16 v[60:63], v[168:171], v[184:187], v[60:63]
	v_mfma_f32_16x16x32_bf16 v[52:55], v[176:179], v[184:187], v[52:55]
	v_mfma_f32_16x16x32_bf16 v[44:47], v[168:171], v[194:197], v[44:47]
	v_mfma_f32_16x16x32_bf16 v[36:39], v[176:179], v[194:197], v[36:39]
	v_mfma_f32_16x16x32_bf16 v[28:31], v[168:171], v[202:205], v[28:31]
	v_mfma_f32_16x16x32_bf16 v[20:23], v[176:179], v[202:205], v[20:23]
	v_mfma_f32_16x16x32_bf16 v[12:15], v[168:171], v[210:213], v[12:15]
	v_mfma_f32_16x16x32_bf16 v[4:7], v[176:179], v[210:213], v[4:7]
	v_mfma_f32_16x16x32_bf16 v[60:63], v[172:175], v[190:193], v[60:63]
	v_mfma_f32_16x16x32_bf16 v[52:55], v[180:183], v[190:193], v[52:55]
	v_mfma_f32_16x16x32_bf16 v[44:47], v[172:175], v[198:201], v[44:47]
	v_mfma_f32_16x16x32_bf16 v[36:39], v[180:183], v[198:201], v[36:39]
	v_mfma_f32_16x16x32_bf16 v[28:31], v[172:175], v[206:209], v[28:31]
	v_mfma_f32_16x16x32_bf16 v[20:23], v[180:183], v[206:209], v[20:23]
	v_mfma_f32_16x16x32_bf16 v[12:15], v[172:175], v[214:217], v[12:15]
	v_mfma_f32_16x16x32_bf16 v[4:7], v[180:183], v[214:217], v[4:7]
	s_setprio 0
	s_barrier
	s_add_i32 s51, s51, 2
	s_add_u32 s22, s22, 0x100
	s_addc_u32 s23, s23, 0
	s_add_u32 s49, s49, 0x100
	s_addc_u32 s50, s50, 0
	.p2alignl 6, 3212836864

; #define PG8_STAGE(bufoff, gbase, voff) do { _Pragma("unroll") for (int _i = 0; _i < 2; ++_i) \
;         __builtin_amdgcn_global_load_lds((const unsigned*)((const char*)(gbase) + (voff)[_i]), (PG8_LAS unsigned*)(lds + (bufoff) + ldsw + _i * 8192), 16, 0, 0); } while (0)
; #define PG8_LDA(dst, b, h) do { _Pragma("unroll") for (int m = 0; m < 4; ++m) _Pragma("unroll") for (int k = 0; k < 2; ++k) dst[m][k] = *(const PG8_LAS bf16x8*)(lds + PG8_SA(b, h) + aoff + m * 2048 + k * 1024); } while (0)
; #define PG8_LDB(dst, b, h) do { _Pragma("unroll") for (int n = 0; n < 2; ++n) _Pragma("unroll") for (int k = 0; k < 2; ++k) dst[n][k] = *(const PG8_LAS bf16x8*)(lds + PG8_SB(b, h) + boff + n * 2048 + k * 1024); } while (0)
; #define PG8_MMA(ai, bj, At, Bt) do { __builtin_amdgcn_s_setprio(1); _Pragma("unroll") for (int m = 0; m < 4; ++m) _Pragma("unroll") for (int n = 0; n < 2; ++n) _Pragma("unroll") for (int k = 0; k < 2; ++k) \
;         acc[ai][bj][m][n] = __builtin_amdgcn_mfma_f32_16x16x32_bf16(Bt[n][k], At[m][k], acc[ai][bj][m][n], 0, 0, 0); __builtin_amdgcn_s_setprio(0); } while (0)
; #define PG8_WAIT_V(n) asm volatile("s_waitcnt vmcnt(" #n ")" ::: "memory")
; #define PG8_WAIT_L(n) asm volatile("s_waitcnt lgkmcnt(" #n ")" ::: "memory")
; #define PG8_BAR __builtin_amdgcn_s_barrier()
; #define PG8_SCHED __builtin_amdgcn_sched_barrier(0)
; template <class Epi, class Sched, bool ALIGN_EPI = false, bool SP2 = false>
; __device__ __forceinline__ void gemm_phase(PG8_LAS unsigned char* lds, const Gemm g, const Sched& S, const Epi& E) {
;     ...
;             PG8_LDB(B0, 0, 0); PG8_LDB(B1, 0, 1); PG8_SCHED; PG8_LDA(At, 0, 0); PG8_STAGE(PG8_SA(1, 1), a1 + hstep, voffA);
;             PG8_WAIT_V(8); PG8_WAIT_L(0); PG8_BAR; PG8_MMA(0, 0, At, B0); PG8_MMA(0, 1, At, B1); PG8_BAR; PG8_SCHED;
;             PG8_LDA(At, 0, 1); PG8_STAGE(PG8_SB(0, 0), b2, voffB); PG8_STAGE(PG8_SB(0, 1), b2 + hstep, voffB); PG8_STAGE(PG8_SA(0, 0), a2, voffA);
;             PG8_WAIT_V(8); PG8_WAIT_L(0); PG8_BAR; PG8_MMA(1, 0, At, B0); PG8_MMA(1, 1, At, B1); PG8_BAR; PG8_SCHED;
.LBB0_861:
	s_add_u32 s49, s24, 0x100
	s_addc_u32 s50, s25, 0
	s_mov_b32 s51, -2
	ds_read_b128 v[144:147], v153
	ds_read_b128 v[156:159], v153 offset:1024
	ds_read_b128 v[160:163], v153 offset:2048
	ds_read_b128 v[164:167], v153 offset:3072
	ds_read_b128 v[168:171], v154
	ds_read_b128 v[172:175], v154 offset:1024
	ds_read_b128 v[176:179], v154 offset:2048
	ds_read_b128 v[180:183], v154 offset:3072
	s_add_u32 s24, s22, 0x100
	s_addc_u32 s25, s23, 0
	s_cmp_eq_u32 s51, 40
	s_cselect_b32 s29, s5, s25
	s_cselect_b32 s28, s4, s24
	s_cselect_b32 s27, s21, s50
	s_cselect_b32 s26, s20, s49
	v_lshl_add_u64 v[148:149], s[22:23], 0, v[136:137]
	s_add_i32 m0, s35, 0xc000
	ds_read_b128 v[184:187], v155
	ds_read_b128 v[188:191], v155 offset:1024
	ds_read_b128 v[192:195], v155 offset:2048
	ds_read_b128 v[196:199], v155 offset:3072
	ds_read_b128 v[200:203], v155 offset:4096
	ds_read_b128 v[204:207], v155 offset:5120
	ds_read_b128 v[208:211], v155 offset:6144
	ds_read_b128 v[212:215], v155 offset:7168
	global_load_lds_dwordx4 v[148:149], off
	v_lshl_add_u64 v[148:149], s[22:23], 0, v[138:139]
	s_add_i32 m0, s35, 0xe000
	s_nop 0
	global_load_lds_dwordx4 v[148:149], off
	s_waitcnt vmcnt(8)
	s_waitcnt lgkmcnt(0)
	s_barrier
	s_setprio 1
	v_mfma_f32_16x16x32_bf16 v[124:127], v[144:147], v[184:187], 0
	v_mfma_f32_16x16x32_bf16 v[120:123], v[160:163], v[184:187], 0
	v_mfma_f32_16x16x32_bf16 v[108:111], v[144:147], v[192:195], 0
	v_mfma_f32_16x16x32_bf16 v[104:107], v[160:163], v[192:195], 0
	v_mfma_f32_16x16x32_bf16 v[92:95], v[144:147], v[200:203], 0
	v_mfma_f32_16x16x32_bf16 v[88:91], v[160:163], v[200:203], 0
	v_mfma_f32_16x16x32_bf16 v[76:79], v[144:147], v[208:211], 0
	v_mfma_f32_16x16x32_bf16 v[72:75], v[160:163], v[208:211], 0
	v_mfma_f32_16x16x32_bf16 v[124:127], v[156:159], v[188:191], v[124:127]
	v_mfma_f32_16x16x32_bf16 v[120:123], v[164:167], v[188:191], v[120:123]
	v_mfma_f32_16x16x32_bf16 v[108:111], v[156:159], v[196:199], v[108:111]
	v_mfma_f32_16x16x32_bf16 v[104:107], v[164:167], v[196:199], v[104:107]
	v_mfma_f32_16x16x32_bf16 v[92:95], v[156:159], v[204:207], v[92:95]
	v_mfma_f32_16x16x32_bf16 v[88:91], v[164:167], v[204:207], v[88:91]
	v_mfma_f32_16x16x32_bf16 v[76:79], v[156:159], v[212:215], v[76:79]
	v_mfma_f32_16x16x32_bf16 v[72:75], v[164:167], v[212:215], v[72:75]
	v_mfma_f32_16x16x32_bf16 v[116:119], v[168:171], v[184:187], 0
	v_mfma_f32_16x16x32_bf16 v[112:115], v[176:179], v[184:187], 0
	v_mfma_f32_16x16x32_bf16 v[100:103], v[168:171], v[192:195], 0
	v_mfma_f32_16x16x32_bf16 v[96:99], v[176:179], v[192:195], 0
	v_mfma_f32_16x16x32_bf16 v[84:87], v[168:171], v[200:203], 0
	v_mfma_f32_16x16x32_bf16 v[80:83], v[176:179], v[200:203], 0
	v_mfma_f32_16x16x32_bf16 v[68:71], v[168:171], v[208:211], 0
	v_mfma_f32_16x16x32_bf16 v[64:67], v[176:179], v[208:211], 0
	v_mfma_f32_16x16x32_bf16 v[116:119], v[172:175], v[188:191], v[116:119]
	v_mfma_f32_16x16x32_bf16 v[112:115], v[180:183], v[188:191], v[112:115]
	v_mfma_f32_16x16x32_bf16 v[100:103], v[172:175], v[196:199], v[100:103]
	v_mfma_f32_16x16x32_bf16 v[96:99], v[180:183], v[196:199], v[96:99]
	v_mfma_f32_16x16x32_bf16 v[84:87], v[172:175], v[204:207], v[84:87]
	v_mfma_f32_16x16x32_bf16 v[80:83], v[180:183], v[204:207], v[80:83]
	v_mfma_f32_16x16x32_bf16 v[68:71], v[172:175], v[212:215], v[68:71]
	v_mfma_f32_16x16x32_bf16 v[64:67], v[180:183], v[212:215], v[64:67]
	s_setprio 0
	s_barrier
	s_add_i32 s22, s43, s34
	v_lshl_add_u64 v[148:149], s[26:27], 0, v[130:131]
	s_mov_b32 m0, s22
	ds_read_b128 v[184:187], v155 offset:16384
	ds_read_b128 v[188:191], v155 offset:17408
	ds_read_b128 v[192:195], v155 offset:18432
	ds_read_b128 v[196:199], v155 offset:19456
	ds_read_b128 v[200:203], v155 offset:20480
	ds_read_b128 v[204:207], v155 offset:21504
	ds_read_b128 v[208:211], v155 offset:22528
	ds_read_b128 v[212:215], v155 offset:23552
	global_load_lds_dwordx4 v[148:149], off
	s_add_i32 m0, s22, 0x2000
	s_add_u32 s22, s26, 0xb0000
	v_lshl_add_u64 v[216:217], s[26:27], 0, v[134:135]
	s_addc_u32 s23, s27, 0
	s_add_i32 s52, s44, s34
	global_load_lds_dwordx4 v[216:217], off
	v_lshl_add_u64 v[218:219], s[22:23], 0, v[130:131]
	s_mov_b32 m0, s52
	v_lshl_add_u64 v[220:221], s[28:29], 0, v[132:133]
	global_load_lds_dwordx4 v[218:219], off
	v_lshl_add_u64 v[218:219], s[22:23], 0, v[134:135]
	s_add_i32 m0, s52, 0x2000
	s_nop 0
	global_load_lds_dwordx4 v[218:219], off
	v_lshl_add_u64 v[218:219], s[28:29], 0, v[128:129]
	s_mov_b32 m0, s35
	s_nop 0
	global_load_lds_dwordx4 v[218:219], off
	s_mov_b32 m0, s36
	s_nop 0
	global_load_lds_dwordx4 v[220:221], off
	s_waitcnt vmcnt(8)
	s_waitcnt lgkmcnt(0)
	s_barrier
; #define PG8_STAGE(bufoff, gbase, voff) do { _Pragma("unroll") for (int _i = 0; _i < 2; ++_i) \
;         __builtin_amdgcn_global_load_lds((const unsigned*)((const char*)(gbase) + (voff)[_i]), (PG8_LAS unsigned*)(lds + (bufoff) + ldsw + _i * 8192), 16, 0, 0); } while (0)
; #define PG8_LDA(dst, b, h) do { _Pragma("unroll") for (int m = 0; m < 4; ++m) _Pragma("unroll") for (int k = 0; k < 2; ++k) dst[m][k] = *(const PG8_LAS bf16x8*)(lds + PG8_SA(b, h) + aoff + m * 2048 + k * 1024); } while (0)
; #define PG8_LDB(dst, b, h) do { _Pragma("unroll") for (int n = 0; n < 2; ++n) _Pragma("unroll") for (int k = 0; k < 2; ++k) dst[n][k] = *(const PG8_LAS bf16x8*)(lds + PG8_SB(b, h) + boff + n * 2048 + k * 1024); } while (0)
; #define PG8_MMA(ai, bj, At, Bt) do { __builtin_amdgcn_s_setprio(1); _Pragma("unroll") for (int m = 0; m < 4; ++m) _Pragma("unroll") for (int n = 0; n < 2; ++n) _Pragma("unroll") for (int k = 0; k < 2; ++k) \
;         acc[ai][bj][m][n] = __builtin_amdgcn_mfma_f32_16x16x32_bf16(Bt[n][k], At[m][k], acc[ai][bj][m][n], 0, 0, 0); __builtin_amdgcn_s_setprio(0); } while (0)
; #define PG8_WAIT_V(n) asm volatile("s_waitcnt vmcnt(" #n ")" ::: "memory")
; #define PG8_WAIT_L(n) asm volatile("s_waitcnt lgkmcnt(" #n ")" ::: "memory")
; #define PG8_BAR __builtin_amdgcn_s_barrier()
; #define PG8_SCHED __builtin_amdgcn_sched_barrier(0)
; template <class Epi, class Sched, bool ALIGN_EPI = false, bool SP2 = false>
; __device__ __forceinline__ void gemm_phase(PG8_LAS unsigned char* lds, const Gemm g, const Sched& S, const Epi& E) {
;     ...
;             PG8_WAIT_V(8); PG8_WAIT_L(0); PG8_BAR; PG8_MMA(1, 0, At, B0); PG8_MMA(1, 1, At, B1); PG8_BAR; PG8_SCHED;
;             PG8_LDB(B0, 1, 0); PG8_LDB(B1, 1, 1); PG8_SCHED; PG8_LDA(At, 1, 0); PG8_STAGE(PG8_SA(0, 1), a2 + hstep, voffA);
;             PG8_WAIT_V(8); PG8_WAIT_L(0); PG8_BAR; PG8_MMA(0, 0, At, B0); PG8_MMA(0, 1, At, B1); PG8_BAR; PG8_SCHED;
	s_setprio 1
	v_mfma_f32_16x16x32_bf16 v[60:63], v[144:147], v[184:187], 0
	v_mfma_f32_16x16x32_bf16 v[56:59], v[160:163], v[184:187], 0
	v_mfma_f32_16x16x32_bf16 v[44:47], v[144:147], v[192:195], 0
	v_mfma_f32_16x16x32_bf16 v[40:43], v[160:163], v[192:195], 0
	v_mfma_f32_16x16x32_bf16 v[28:31], v[144:147], v[200:203], 0
	v_mfma_f32_16x16x32_bf16 v[24:27], v[160:163], v[200:203], 0
	v_mfma_f32_16x16x32_bf16 v[12:15], v[144:147], v[208:211], 0
	v_mfma_f32_16x16x32_bf16 v[8:11], v[160:163], v[208:211], 0
	v_mfma_f32_16x16x32_bf16 v[60:63], v[156:159], v[188:191], v[60:63]
	v_mfma_f32_16x16x32_bf16 v[56:59], v[164:167], v[188:191], v[56:59]
	v_mfma_f32_16x16x32_bf16 v[44:47], v[156:159], v[196:199], v[44:47]
	v_mfma_f32_16x16x32_bf16 v[40:43], v[164:167], v[196:199], v[40:43]
	v_mfma_f32_16x16x32_bf16 v[28:31], v[156:159], v[204:207], v[28:31]
	v_mfma_f32_16x16x32_bf16 v[24:27], v[164:167], v[204:207], v[24:27]
	v_mfma_f32_16x16x32_bf16 v[12:15], v[156:159], v[212:215], v[12:15]
	v_mfma_f32_16x16x32_bf16 v[8:11], v[164:167], v[212:215], v[8:11]
	v_mfma_f32_16x16x32_bf16 v[52:55], v[168:171], v[184:187], 0
	v_mfma_f32_16x16x32_bf16 v[48:51], v[176:179], v[184:187], 0
	v_mfma_f32_16x16x32_bf16 v[36:39], v[168:171], v[192:195], 0
	v_mfma_f32_16x16x32_bf16 v[32:35], v[176:179], v[192:195], 0
	v_mfma_f32_16x16x32_bf16 v[20:23], v[168:171], v[200:203], 0
	v_mfma_f32_16x16x32_bf16 v[16:19], v[176:179], v[200:203], 0
	v_mfma_f32_16x16x32_bf16 v[4:7], v[168:171], v[208:211], 0
	v_mfma_f32_16x16x32_bf16 v[0:3], v[176:179], v[208:211], 0
	v_mfma_f32_16x16x32_bf16 v[52:55], v[172:175], v[188:191], v[52:55]
	v_mfma_f32_16x16x32_bf16 v[48:51], v[180:183], v[188:191], v[48:51]
	v_mfma_f32_16x16x32_bf16 v[36:39], v[172:175], v[196:199], v[36:39]
	v_mfma_f32_16x16x32_bf16 v[32:35], v[180:183], v[196:199], v[32:35]
	v_mfma_f32_16x16x32_bf16 v[20:23], v[172:175], v[204:207], v[20:23]
	v_mfma_f32_16x16x32_bf16 v[16:19], v[180:183], v[204:207], v[16:19]
	v_mfma_f32_16x16x32_bf16 v[4:7], v[172:175], v[212:215], v[4:7]
	v_mfma_f32_16x16x32_bf16 v[0:3], v[180:183], v[212:215], v[0:3]
	s_setprio 0
	s_barrier
	s_add_i32 s52, 0, 0x18000
	s_add_i32 s53, 0, 0x1c000
	v_add_u32_e32 v164, s52, v151
	v_add_u32_e32 v180, s53, v151
	ds_read_b128 v[144:147], v164
	ds_read_b128 v[156:159], v164 offset:1024
	ds_read_b128 v[160:163], v164 offset:2048
	ds_read_b128 v[164:167], v164 offset:3072
	ds_read_b128 v[168:171], v180
	ds_read_b128 v[172:175], v180 offset:1024
	ds_read_b128 v[176:179], v180 offset:2048
	ds_read_b128 v[180:183], v180 offset:3072
	s_add_u32 s22, s28, 0xb0000
	s_addc_u32 s23, s29, 0
	s_mov_b32 m0, s37
	v_lshl_add_u64 v[222:223], s[22:23], 0, v[128:129]
	ds_read_b128 v[184:187], v155 offset:32768
	ds_read_b128 v[188:191], v155 offset:33792
	ds_read_b128 v[192:195], v155 offset:34816
	ds_read_b128 v[196:199], v155 offset:35840
	ds_read_b128 v[200:203], v155 offset:36864
	ds_read_b128 v[204:207], v155 offset:37888
	ds_read_b128 v[208:211], v155 offset:38912
	ds_read_b128 v[212:215], v155 offset:39936
	global_load_lds_dwordx4 v[222:223], off
	v_lshl_add_u64 v[222:223], s[22:23], 0, v[132:133]
	s_mov_b32 m0, s38
	s_nop 0
	global_load_lds_dwordx4 v[222:223], off
	s_waitcnt vmcnt(8)
	s_waitcnt lgkmcnt(0)
	s_barrier
	s_setprio 1
	v_mfma_f32_16x16x32_bf16 v[124:127], v[144:147], v[184:187], v[124:127]
	v_mfma_f32_16x16x32_bf16 v[120:123], v[160:163], v[184:187], v[120:123]
	v_mfma_f32_16x16x32_bf16 v[108:111], v[144:147], v[192:195], v[108:111]
	v_mfma_f32_16x16x32_bf16 v[104:107], v[160:163], v[192:195], v[104:107]
	v_mfma_f32_16x16x32_bf16 v[92:95], v[144:147], v[200:203], v[92:95]
	v_mfma_f32_16x16x32_bf16 v[88:91], v[160:163], v[200:203], v[88:91]
	v_mfma_f32_16x16x32_bf16 v[76:79], v[144:147], v[208:211], v[76:79]
	v_mfma_f32_16x16x32_bf16 v[72:75], v[160:163], v[208:211], v[72:75]
	v_mfma_f32_16x16x32_bf16 v[124:127], v[156:159], v[188:191], v[124:127]
	v_mfma_f32_16x16x32_bf16 v[120:123], v[164:167], v[188:191], v[120:123]
	v_mfma_f32_16x16x32_bf16 v[108:111], v[156:159], v[196:199], v[108:111]
	v_mfma_f32_16x16x32_bf16 v[104:107], v[164:167], v[196:199], v[104:107]
	v_mfma_f32_16x16x32_bf16 v[92:95], v[156:159], v[204:207], v[92:95]
	v_mfma_f32_16x16x32_bf16 v[88:91], v[164:167], v[204:207], v[88:91]
	v_mfma_f32_16x16x32_bf16 v[76:79], v[156:159], v[212:215], v[76:79]
	v_mfma_f32_16x16x32_bf16 v[72:75], v[164:167], v[212:215], v[72:75]
	v_mfma_f32_16x16x32_bf16 v[116:119], v[168:171], v[184:187], v[116:119]
	v_mfma_f32_16x16x32_bf16 v[112:115], v[176:179], v[184:187], v[112:115]
	v_mfma_f32_16x16x32_bf16 v[100:103], v[168:171], v[192:195], v[100:103]
	v_mfma_f32_16x16x32_bf16 v[96:99], v[176:179], v[192:195], v[96:99]
	v_mfma_f32_16x16x32_bf16 v[84:87], v[168:171], v[200:203], v[84:87]
	v_mfma_f32_16x16x32_bf16 v[80:83], v[176:179], v[200:203], v[80:83]
	v_mfma_f32_16x16x32_bf16 v[68:71], v[168:171], v[208:211], v[68:71]
	v_mfma_f32_16x16x32_bf16 v[64:67], v[176:179], v[208:211], v[64:67]
	v_mfma_f32_16x16x32_bf16 v[116:119], v[172:175], v[188:191], v[116:119]
	v_mfma_f32_16x16x32_bf16 v[112:115], v[180:183], v[188:191], v[112:115]
	v_mfma_f32_16x16x32_bf16 v[100:103], v[172:175], v[196:199], v[100:103]
	v_mfma_f32_16x16x32_bf16 v[96:99], v[180:183], v[196:199], v[96:99]
	v_mfma_f32_16x16x32_bf16 v[84:87], v[172:175], v[204:207], v[84:87]
	v_mfma_f32_16x16x32_bf16 v[80:83], v[180:183], v[204:207], v[80:83]
	v_mfma_f32_16x16x32_bf16 v[68:71], v[172:175], v[212:215], v[68:71]
	v_mfma_f32_16x16x32_bf16 v[64:67], v[180:183], v[212:215], v[64:67]
	s_setprio 0
	s_barrier
; #define PG8_STAGE(bufoff, gbase, voff) do { _Pragma("unroll") for (int _i = 0; _i < 2; ++_i) \
;         __builtin_amdgcn_global_load_lds((const unsigned*)((const char*)(gbase) + (voff)[_i]), (PG8_LAS unsigned*)(lds + (bufoff) + ldsw + _i * 8192), 16, 0, 0); } while (0)
; #define PG8_LDA(dst, b, h) do { _Pragma("unroll") for (int m = 0; m < 4; ++m) _Pragma("unroll") for (int k = 0; k < 2; ++k) dst[m][k] = *(const PG8_LAS bf16x8*)(lds + PG8_SA(b, h) + aoff + m * 2048 + k * 1024); } while (0)
; #define PG8_MMA(ai, bj, At, Bt) do { __builtin_amdgcn_s_setprio(1); _Pragma("unroll") for (int m = 0; m < 4; ++m) _Pragma("unroll") for (int n = 0; n < 2; ++n) _Pragma("unroll") for (int k = 0; k < 2; ++k) \
;         acc[ai][bj][m][n] = __builtin_amdgcn_mfma_f32_16x16x32_bf16(Bt[n][k], At[m][k], acc[ai][bj][m][n], 0, 0, 0); __builtin_amdgcn_s_setprio(0); } while (0)
; #define PG8_WAIT_V(n) asm volatile("s_waitcnt vmcnt(" #n ")" ::: "memory")
; #define PG8_WAIT_L(n) asm volatile("s_waitcnt lgkmcnt(" #n ")" ::: "memory")
; #define PG8_BAR __builtin_amdgcn_s_barrier()
; #define PG8_SCHED __builtin_amdgcn_sched_barrier(0)
; template <class Epi, class Sched, bool ALIGN_EPI = false, bool SP2 = false>
; __device__ __forceinline__ void gemm_phase(PG8_LAS unsigned char* lds, const Gemm g, const Sched& S, const Epi& E) {
;     ...
;             PG8_LDA(At, 1, 1); PG8_STAGE(PG8_SB(1, 0), b3, voffB); PG8_STAGE(PG8_SB(1, 1), b3 + hstep, voffB); PG8_STAGE(PG8_SA(1, 0), a3, voffA);
;             PG8_WAIT_V(8); PG8_WAIT_L(0); PG8_BAR; PG8_MMA(1, 0, At, B0); PG8_MMA(1, 1, At, B1); PG8_BAR; PG8_SCHED;
	s_add_i32 s22, s52, s34
	v_lshl_add_u64 v[148:149], v[148:149], 0, s[6:7]
	s_mov_b32 m0, s22
	ds_read_b128 v[184:187], v155 offset:49152
	ds_read_b128 v[188:191], v155 offset:50176
	ds_read_b128 v[192:195], v155 offset:51200
	ds_read_b128 v[196:199], v155 offset:52224
	ds_read_b128 v[200:203], v155 offset:53248
	ds_read_b128 v[204:207], v155 offset:54272
	ds_read_b128 v[208:211], v155 offset:55296
	ds_read_b128 v[212:215], v155 offset:56320
	global_load_lds_dwordx4 v[148:149], off
	s_add_i32 m0, s22, 0x2000
	s_add_u32 s22, s26, 0xb0080
	v_lshl_add_u64 v[148:149], v[216:217], 0, s[6:7]
	s_addc_u32 s23, s27, 0
	s_add_i32 s26, s53, s34
	global_load_lds_dwordx4 v[148:149], off
	v_lshl_add_u64 v[148:149], s[22:23], 0, v[130:131]
	s_mov_b32 m0, s26
	s_nop 0
	global_load_lds_dwordx4 v[148:149], off
	v_lshl_add_u64 v[148:149], s[22:23], 0, v[134:135]
	s_add_i32 m0, s26, 0x2000
	s_nop 0
	global_load_lds_dwordx4 v[148:149], off
	v_lshl_add_u64 v[148:149], v[218:219], 0, s[6:7]
	s_mov_b32 m0, s40
	s_nop 0
	global_load_lds_dwordx4 v[148:149], off
	v_lshl_add_u64 v[148:149], v[220:221], 0, s[6:7]
	s_mov_b32 m0, s41
	s_nop 0
	global_load_lds_dwordx4 v[148:149], off
	s_waitcnt vmcnt(8)
	s_waitcnt lgkmcnt(0)
	s_barrier
	s_setprio 1
	v_mfma_f32_16x16x32_bf16 v[60:63], v[144:147], v[184:187], v[60:63]
	v_mfma_f32_16x16x32_bf16 v[56:59], v[160:163], v[184:187], v[56:59]
	v_mfma_f32_16x16x32_bf16 v[44:47], v[144:147], v[192:195], v[44:47]
	v_mfma_f32_16x16x32_bf16 v[40:43], v[160:163], v[192:195], v[40:43]
	v_mfma_f32_16x16x32_bf16 v[28:31], v[144:147], v[200:203], v[28:31]
	v_mfma_f32_16x16x32_bf16 v[24:27], v[160:163], v[200:203], v[24:27]
	v_mfma_f32_16x16x32_bf16 v[12:15], v[144:147], v[208:211], v[12:15]
	v_mfma_f32_16x16x32_bf16 v[8:11], v[160:163], v[208:211], v[8:11]
	v_mfma_f32_16x16x32_bf16 v[60:63], v[156:159], v[188:191], v[60:63]
	v_mfma_f32_16x16x32_bf16 v[56:59], v[164:167], v[188:191], v[56:59]
	v_mfma_f32_16x16x32_bf16 v[44:47], v[156:159], v[196:199], v[44:47]
	v_mfma_f32_16x16x32_bf16 v[40:43], v[164:167], v[196:199], v[40:43]
	v_mfma_f32_16x16x32_bf16 v[28:31], v[156:159], v[204:207], v[28:31]
	v_mfma_f32_16x16x32_bf16 v[24:27], v[164:167], v[204:207], v[24:27]
	v_mfma_f32_16x16x32_bf16 v[12:15], v[156:159], v[212:215], v[12:15]
	v_mfma_f32_16x16x32_bf16 v[8:11], v[164:167], v[212:215], v[8:11]
	v_mfma_f32_16x16x32_bf16 v[52:55], v[168:171], v[184:187], v[52:55]
	v_mfma_f32_16x16x32_bf16 v[48:51], v[176:179], v[184:187], v[48:51]
	v_mfma_f32_16x16x32_bf16 v[36:39], v[168:171], v[192:195], v[36:39]
	v_mfma_f32_16x16x32_bf16 v[32:35], v[176:179], v[192:195], v[32:35]
	v_mfma_f32_16x16x32_bf16 v[20:23], v[168:171], v[200:203], v[20:23]
	v_mfma_f32_16x16x32_bf16 v[16:19], v[176:179], v[200:203], v[16:19]
	v_mfma_f32_16x16x32_bf16 v[4:7], v[168:171], v[208:211], v[4:7]
	v_mfma_f32_16x16x32_bf16 v[0:3], v[176:179], v[208:211], v[0:3]
	v_mfma_f32_16x16x32_bf16 v[52:55], v[172:175], v[188:191], v[52:55]
	v_mfma_f32_16x16x32_bf16 v[48:51], v[180:183], v[188:191], v[48:51]
	v_mfma_f32_16x16x32_bf16 v[36:39], v[172:175], v[196:199], v[36:39]
	v_mfma_f32_16x16x32_bf16 v[32:35], v[180:183], v[196:199], v[32:35]
	v_mfma_f32_16x16x32_bf16 v[20:23], v[172:175], v[204:207], v[20:23]
	v_mfma_f32_16x16x32_bf16 v[16:19], v[180:183], v[204:207], v[16:19]
	v_mfma_f32_16x16x32_bf16 v[4:7], v[172:175], v[212:215], v[4:7]
	v_mfma_f32_16x16x32_bf16 v[0:3], v[180:183], v[212:215], v[0:3]
	s_setprio 0
	s_barrier
	s_add_i32 s51, s51, 2
	s_add_u32 s49, s49, 0x100
	s_addc_u32 s50, s50, 0
	s_mov_b64 s[22:23], s[24:25]
	.p2alignl 6, 3212836864
